# P1b epilogue: w0/a0 row loaded once per unit before the closing K-loop barrier instead of 16 load+vmcnt(0) round trips; orphan s_nops from the division rewrite removed
# speedup vs baseline: 1.0056x; 1.0056x over previous
.LBB0_330:
	s_ashr_i32 s35, s34, 31
	s_lshl_b64 s[0:1], s[34:35], 16
	s_add_u32 s58, s52, s0
	s_addc_u32 s59, s53, s1
	s_and_b64 s[0:1], s[6:7], exec
	s_cselect_b32 s5, s59, s37
	s_cselect_b32 s4, s58, s36
	s_ashr_i32 s31, s30, 31
	s_lshl_b64 s[0:1], s[30:31], 16
	s_add_u32 s38, s12, s0
	s_addc_u32 s39, s13, s1
	s_add_u32 s0, s36, 0x8080
	ds_read_b128 v[0:3], v153
	ds_read_b128 v[4:7], v153 offset:1024
	ds_read_b128 v[8:11], v153 offset:2048
	ds_read_b128 v[12:15], v153 offset:3072
	ds_read_b128 v[16:19], v154
	ds_read_b128 v[20:23], v154 offset:1024
	ds_read_b128 v[24:27], v154 offset:2048
	ds_read_b128 v[28:31], v154 offset:3072
	s_addc_u32 s1, s37, 0
	s_add_u32 s36, s4, 0x8000
	s_addc_u32 s37, s5, 0
	s_and_b64 s[18:19], s[6:7], exec
	s_cselect_b32 s8, s38, s8
	s_cselect_b32 s9, s39, s9
	s_add_u32 s18, s8, 0x8000
	s_addc_u32 s19, s9, 0
	v_lshl_add_u64 v[64:65], s[0:1], 0, v[128:129]
	s_add_i32 m0, s40, 0xc000
	ds_read_b128 v[32:35], v155
	ds_read_b128 v[36:39], v155 offset:1024
	ds_read_b128 v[40:43], v155 offset:2048
	ds_read_b128 v[44:47], v155 offset:3072
	ds_read_b128 v[48:51], v155 offset:4096
	ds_read_b128 v[52:55], v155 offset:5120
	ds_read_b128 v[56:59], v155 offset:6144
	ds_read_b128 v[60:63], v155 offset:7168
	global_load_lds_dwordx4 v[64:65], off
	v_lshl_add_u64 v[64:65], s[0:1], 0, v[132:133]
	s_add_i32 m0, s40, 0xe000
	s_nop 0
	global_load_lds_dwordx4 v[64:65], off
	s_waitcnt vmcnt(8)
	s_waitcnt lgkmcnt(0)
	s_barrier
	s_setprio 1
	s_waitcnt lgkmcnt(0)
	v_mfma_f32_16x16x32_bf16 v[88:91], v[0:3], v[56:59], 0
	v_mfma_f32_16x16x32_bf16 v[64:67], v[0:3], v[32:35], 0
	v_mfma_f32_16x16x32_bf16 v[68:71], v[8:11], v[32:35], 0
	v_mfma_f32_16x16x32_bf16 v[72:75], v[0:3], v[40:43], 0
	v_mfma_f32_16x16x32_bf16 v[76:79], v[8:11], v[40:43], 0
	v_mfma_f32_16x16x32_bf16 v[80:83], v[0:3], v[48:51], 0
	v_mfma_f32_16x16x32_bf16 v[84:87], v[8:11], v[48:51], 0
	v_mfma_f32_16x16x32_bf16 v[96:99], v[4:7], v[60:63], v[88:91]
	v_mfma_f32_16x16x32_bf16 v[88:91], v[8:11], v[56:59], 0
	v_mfma_f32_16x16x32_bf16 v[64:67], v[4:7], v[36:39], v[64:67]
	v_mfma_f32_16x16x32_bf16 v[68:71], v[12:15], v[36:39], v[68:71]
	v_mfma_f32_16x16x32_bf16 v[72:75], v[4:7], v[44:47], v[72:75]
	v_mfma_f32_16x16x32_bf16 v[76:79], v[12:15], v[44:47], v[76:79]
	v_mfma_f32_16x16x32_bf16 v[80:83], v[4:7], v[52:55], v[80:83]
	v_mfma_f32_16x16x32_bf16 v[84:87], v[12:15], v[52:55], v[84:87]
	v_mfma_f32_16x16x32_bf16 v[100:103], v[12:15], v[60:63], v[88:91]
	s_setprio 0
	s_setprio 1
	v_mfma_f32_16x16x32_bf16 v[88:91], v[16:19], v[32:35], 0
	v_mfma_f32_16x16x32_bf16 v[32:35], v[24:27], v[32:35], 0
	v_mfma_f32_16x16x32_bf16 v[112:115], v[20:23], v[36:39], v[88:91]
	v_mfma_f32_16x16x32_bf16 v[32:35], v[28:31], v[36:39], v[32:35]
	v_mfma_f32_16x16x32_bf16 v[36:39], v[16:19], v[40:43], 0
	v_mfma_f32_16x16x32_bf16 v[40:43], v[24:27], v[40:43], 0
	v_mfma_f32_16x16x32_bf16 v[36:39], v[20:23], v[44:47], v[36:39]
	v_mfma_f32_16x16x32_bf16 v[40:43], v[28:31], v[44:47], v[40:43]
	v_mfma_f32_16x16x32_bf16 v[44:47], v[16:19], v[48:51], 0
	v_mfma_f32_16x16x32_bf16 v[48:51], v[24:27], v[48:51], 0
	v_mfma_f32_16x16x32_bf16 v[44:47], v[20:23], v[52:55], v[44:47]
	v_mfma_f32_16x16x32_bf16 v[48:51], v[28:31], v[52:55], v[48:51]
	v_mfma_f32_16x16x32_bf16 v[52:55], v[16:19], v[56:59], 0
	v_mfma_f32_16x16x32_bf16 v[56:59], v[24:27], v[56:59], 0
	v_mfma_f32_16x16x32_bf16 v[52:55], v[20:23], v[60:63], v[52:55]
	v_mfma_f32_16x16x32_bf16 v[56:59], v[28:31], v[60:63], v[56:59]
	s_setprio 0
	s_barrier
	s_add_i32 s0, s20, s29
	v_lshl_add_u64 v[224:225], s[8:9], 0, v[130:131]
	s_mov_b32 m0, s0
	ds_read_b128 v[60:63], v155 offset:16384
	ds_read_b128 v[88:91], v155 offset:17408
	ds_read_b128 v[92:95], v155 offset:18432
	ds_read_b128 v[104:107], v155 offset:19456
	ds_read_b128 v[108:111], v155 offset:20480
	ds_read_b128 v[116:119], v155 offset:21504
	ds_read_b128 v[120:123], v155 offset:22528
	ds_read_b128 v[124:127], v155 offset:23552
	global_load_lds_dwordx4 v[224:225], off
	v_lshl_add_u64 v[248:249], s[8:9], 0, v[134:135]
	s_add_i32 m0, s0, 0x2000
	s_add_i32 s0, s21, s29
	global_load_lds_dwordx4 v[248:249], off
	v_lshl_add_u64 v[142:143], s[18:19], 0, v[130:131]
	s_mov_b32 m0, s0
	v_lshl_add_u64 v[250:251], s[4:5], 0, v[128:129]
	global_load_lds_dwordx4 v[142:143], off
	v_lshl_add_u64 v[142:143], s[18:19], 0, v[134:135]
	s_add_i32 m0, s0, 0x2000
	v_lshl_add_u64 v[252:253], s[4:5], 0, v[132:133]
	global_load_lds_dwordx4 v[142:143], off
	s_mov_b32 m0, s40
	s_nop 0
	global_load_lds_dwordx4 v[250:251], off
	s_mov_b32 m0, s41
	s_nop 0
	global_load_lds_dwordx4 v[252:253], off
	s_waitcnt vmcnt(8)
	s_waitcnt lgkmcnt(0)
	s_barrier
	s_setprio 1
	s_waitcnt lgkmcnt(0)
	v_mfma_f32_16x16x32_bf16 v[142:145], v[0:3], v[60:63], 0
	v_mfma_f32_16x16x32_bf16 v[156:159], v[0:3], v[92:95], 0
	v_mfma_f32_16x16x32_bf16 v[164:167], v[0:3], v[108:111], 0
	v_mfma_f32_16x16x32_bf16 v[0:3], v[0:3], v[120:123], 0
	v_mfma_f32_16x16x32_bf16 v[142:145], v[4:7], v[88:91], v[142:145]
	v_mfma_f32_16x16x32_bf16 v[156:159], v[4:7], v[104:107], v[156:159]
	v_mfma_f32_16x16x32_bf16 v[164:167], v[4:7], v[116:119], v[164:167]
	v_mfma_f32_16x16x32_bf16 v[0:3], v[4:7], v[124:127], v[0:3]
	v_mfma_f32_16x16x32_bf16 v[4:7], v[8:11], v[120:123], 0
	v_mfma_f32_16x16x32_bf16 v[146:149], v[8:11], v[60:63], 0
	v_mfma_f32_16x16x32_bf16 v[160:163], v[8:11], v[92:95], 0
	v_mfma_f32_16x16x32_bf16 v[168:171], v[8:11], v[108:111], 0
	v_mfma_f32_16x16x32_bf16 v[4:7], v[12:15], v[124:127], v[4:7]
	v_mfma_f32_16x16x32_bf16 v[146:149], v[12:15], v[88:91], v[146:149]
	v_mfma_f32_16x16x32_bf16 v[160:163], v[12:15], v[104:107], v[160:163]
	v_mfma_f32_16x16x32_bf16 v[168:171], v[12:15], v[116:119], v[168:171]
	s_setprio 0
	s_setprio 1
	v_mfma_f32_16x16x32_bf16 v[8:11], v[16:19], v[60:63], 0
	v_mfma_f32_16x16x32_bf16 v[172:175], v[20:23], v[88:91], v[8:11]
	v_mfma_f32_16x16x32_bf16 v[8:11], v[24:27], v[60:63], 0
	v_mfma_f32_16x16x32_bf16 v[176:179], v[28:31], v[88:91], v[8:11]
	v_mfma_f32_16x16x32_bf16 v[8:11], v[16:19], v[92:95], 0
	v_mfma_f32_16x16x32_bf16 v[180:183], v[20:23], v[104:107], v[8:11]
	v_mfma_f32_16x16x32_bf16 v[8:11], v[24:27], v[92:95], 0
	v_mfma_f32_16x16x32_bf16 v[184:187], v[28:31], v[104:107], v[8:11]
	v_mfma_f32_16x16x32_bf16 v[8:11], v[16:19], v[108:111], 0
	v_mfma_f32_16x16x32_bf16 v[188:191], v[20:23], v[116:119], v[8:11]
	v_mfma_f32_16x16x32_bf16 v[8:11], v[24:27], v[108:111], 0
	v_mfma_f32_16x16x32_bf16 v[192:195], v[28:31], v[116:119], v[8:11]
	v_mfma_f32_16x16x32_bf16 v[8:11], v[16:19], v[120:123], 0
	v_mfma_f32_16x16x32_bf16 v[196:199], v[20:23], v[124:127], v[8:11]
	v_mfma_f32_16x16x32_bf16 v[8:11], v[24:27], v[120:123], 0
	v_mfma_f32_16x16x32_bf16 v[200:203], v[28:31], v[124:127], v[8:11]
	s_setprio 0
	s_barrier
	s_add_i32 s0, 0, 0x18000
	s_add_i32 s4, 0, 0x1c000
	v_add_u32_e32 v20, s0, v151
	v_add_u32_e32 v24, s4, v151
	s_nop 0
	ds_read_b128 v[8:11], v20
	ds_read_b128 v[12:15], v20 offset:1024
	ds_read_b128 v[16:19], v20 offset:2048
	ds_read_b128 v[20:23], v20 offset:3072
	ds_read_b128 v[204:207], v24
	ds_read_b128 v[208:211], v24 offset:1024
	ds_read_b128 v[212:215], v24 offset:2048
	ds_read_b128 v[216:219], v24 offset:3072
	s_mov_b32 m0, s42
	v_lshl_add_u64 v[88:89], s[36:37], 0, v[128:129]
	ds_read_b128 v[24:27], v155 offset:32768
	ds_read_b128 v[28:31], v155 offset:33792
	ds_read_b128 v[60:63], v155 offset:34816
	ds_read_b128 v[220:223], v155 offset:35840
	ds_read_b128 v[228:231], v155 offset:36864
	ds_read_b128 v[232:235], v155 offset:37888
	ds_read_b128 v[236:239], v155 offset:38912
	ds_read_b128 v[240:243], v155 offset:39936
	global_load_lds_dwordx4 v[88:89], off
	v_lshl_add_u64 v[88:89], s[36:37], 0, v[132:133]
	s_mov_b32 m0, s43
	s_nop 0
	global_load_lds_dwordx4 v[88:89], off
	s_waitcnt vmcnt(8)
	s_waitcnt lgkmcnt(0)
	s_barrier
	s_setprio 1
	s_waitcnt lgkmcnt(0)
	v_mfma_f32_16x16x32_bf16 v[64:67], v[8:11], v[24:27], v[64:67]
	v_mfma_f32_16x16x32_bf16 v[124:127], v[12:15], v[28:31], v[64:67]
	v_mfma_f32_16x16x32_bf16 v[64:67], v[16:19], v[24:27], v[68:71]
	v_mfma_f32_16x16x32_bf16 v[120:123], v[20:23], v[28:31], v[64:67]
	v_mfma_f32_16x16x32_bf16 v[64:67], v[8:11], v[60:63], v[72:75]
	v_mfma_f32_16x16x32_bf16 v[108:111], v[12:15], v[220:223], v[64:67]
	v_mfma_f32_16x16x32_bf16 v[64:67], v[16:19], v[60:63], v[76:79]
	v_mfma_f32_16x16x32_bf16 v[104:107], v[20:23], v[220:223], v[64:67]
	v_mfma_f32_16x16x32_bf16 v[64:67], v[8:11], v[228:231], v[80:83]
	v_mfma_f32_16x16x32_bf16 v[92:95], v[12:15], v[232:235], v[64:67]
	v_mfma_f32_16x16x32_bf16 v[64:67], v[16:19], v[228:231], v[84:87]
	v_mfma_f32_16x16x32_bf16 v[88:91], v[20:23], v[232:235], v[64:67]
	v_mfma_f32_16x16x32_bf16 v[64:67], v[8:11], v[236:239], v[96:99]
	v_mfma_f32_16x16x32_bf16 v[76:79], v[12:15], v[240:243], v[64:67]
	v_mfma_f32_16x16x32_bf16 v[64:67], v[16:19], v[236:239], v[100:103]
	v_mfma_f32_16x16x32_bf16 v[72:75], v[20:23], v[240:243], v[64:67]
	s_setprio 0
	s_setprio 1
	v_mfma_f32_16x16x32_bf16 v[64:67], v[204:207], v[24:27], v[112:115]
	v_mfma_f32_16x16x32_bf16 v[24:27], v[212:215], v[24:27], v[32:35]
	v_mfma_f32_16x16x32_bf16 v[112:115], v[216:219], v[28:31], v[24:27]
	v_mfma_f32_16x16x32_bf16 v[24:27], v[204:207], v[60:63], v[36:39]
	v_mfma_f32_16x16x32_bf16 v[100:103], v[208:211], v[220:223], v[24:27]
	v_mfma_f32_16x16x32_bf16 v[24:27], v[212:215], v[60:63], v[40:43]
	v_mfma_f32_16x16x32_bf16 v[96:99], v[216:219], v[220:223], v[24:27]
	v_mfma_f32_16x16x32_bf16 v[24:27], v[204:207], v[228:231], v[44:47]
	v_mfma_f32_16x16x32_bf16 v[84:87], v[208:211], v[232:235], v[24:27]
	v_mfma_f32_16x16x32_bf16 v[24:27], v[212:215], v[228:231], v[48:51]
	v_mfma_f32_16x16x32_bf16 v[80:83], v[216:219], v[232:235], v[24:27]
	v_mfma_f32_16x16x32_bf16 v[24:27], v[204:207], v[236:239], v[52:55]
	v_mfma_f32_16x16x32_bf16 v[68:71], v[208:211], v[240:243], v[24:27]
	v_mfma_f32_16x16x32_bf16 v[24:27], v[212:215], v[236:239], v[56:59]
	v_mfma_f32_16x16x32_bf16 v[116:119], v[208:211], v[28:31], v[64:67]
	v_mfma_f32_16x16x32_bf16 v[64:67], v[216:219], v[240:243], v[24:27]
	s_setprio 0
	s_barrier
	s_add_i32 s0, s0, s29
	s_nop 2
	v_lshl_add_u64 v[24:25], v[224:225], 0, s[22:23]
	s_mov_b32 m0, s0
	ds_read_b128 v[32:35], v155 offset:49152
	ds_read_b128 v[36:39], v155 offset:50176
	ds_read_b128 v[220:223], v155 offset:51200
	ds_read_b128 v[228:231], v155 offset:52224
	ds_read_b128 v[232:235], v155 offset:53248
	ds_read_b128 v[236:239], v155 offset:54272
	ds_read_b128 v[240:243], v155 offset:55296
	ds_read_b128 v[244:247], v155 offset:56320
	global_load_lds_dwordx4 v[24:25], off
	s_add_i32 m0, s0, 0x2000
	s_add_u32 s0, s8, 0x8080
	v_lshl_add_u64 v[24:25], v[248:249], 0, s[22:23]
	s_addc_u32 s1, s9, 0
	s_add_i32 s4, s4, s29
	global_load_lds_dwordx4 v[24:25], off
	v_lshl_add_u64 v[24:25], s[0:1], 0, v[130:131]
	s_mov_b32 m0, s4
	s_nop 0
	global_load_lds_dwordx4 v[24:25], off
	v_lshl_add_u64 v[24:25], s[0:1], 0, v[134:135]
	s_add_i32 m0, s4, 0x2000
	s_nop 0
	global_load_lds_dwordx4 v[24:25], off
	v_lshl_add_u64 v[24:25], v[250:251], 0, s[22:23]
	s_mov_b32 m0, s44
	s_nop 0
	global_load_lds_dwordx4 v[24:25], off
	v_lshl_add_u64 v[24:25], v[252:253], 0, s[22:23]
	s_mov_b32 m0, s45
	s_nop 0
	global_load_lds_dwordx4 v[24:25], off
	s_waitcnt vmcnt(8)
	s_waitcnt lgkmcnt(0)
	s_barrier
	s_setprio 1
	s_waitcnt lgkmcnt(0)
	v_mfma_f32_16x16x32_bf16 v[24:27], v[8:11], v[32:35], v[142:145]
	v_mfma_f32_16x16x32_bf16 v[60:63], v[12:15], v[36:39], v[24:27]
	v_mfma_f32_16x16x32_bf16 v[24:27], v[16:19], v[32:35], v[146:149]
	v_mfma_f32_16x16x32_bf16 v[56:59], v[20:23], v[36:39], v[24:27]
	v_mfma_f32_16x16x32_bf16 v[24:27], v[8:11], v[220:223], v[156:159]
	v_mfma_f32_16x16x32_bf16 v[44:47], v[12:15], v[228:231], v[24:27]
	v_mfma_f32_16x16x32_bf16 v[24:27], v[16:19], v[220:223], v[160:163]
	v_mfma_f32_16x16x32_bf16 v[40:43], v[20:23], v[228:231], v[24:27]
	v_mfma_f32_16x16x32_bf16 v[24:27], v[8:11], v[232:235], v[164:167]
	v_mfma_f32_16x16x32_bf16 v[0:3], v[8:11], v[240:243], v[0:3]
	v_mfma_f32_16x16x32_bf16 v[28:31], v[12:15], v[236:239], v[24:27]
	v_mfma_f32_16x16x32_bf16 v[24:27], v[16:19], v[232:235], v[168:171]
	v_mfma_f32_16x16x32_bf16 v[12:15], v[12:15], v[244:247], v[0:3]
	v_mfma_f32_16x16x32_bf16 v[0:3], v[16:19], v[240:243], v[4:7]
	v_mfma_f32_16x16x32_bf16 v[24:27], v[20:23], v[236:239], v[24:27]
	v_mfma_f32_16x16x32_bf16 v[8:11], v[20:23], v[244:247], v[0:3]
	s_setprio 0
	s_setprio 1
	v_mfma_f32_16x16x32_bf16 v[0:3], v[204:207], v[32:35], v[172:175]
	v_mfma_f32_16x16x32_bf16 v[52:55], v[208:211], v[36:39], v[0:3]
	v_mfma_f32_16x16x32_bf16 v[0:3], v[212:215], v[32:35], v[176:179]
	v_mfma_f32_16x16x32_bf16 v[48:51], v[216:219], v[36:39], v[0:3]
	v_mfma_f32_16x16x32_bf16 v[0:3], v[204:207], v[220:223], v[180:183]
	v_mfma_f32_16x16x32_bf16 v[36:39], v[208:211], v[228:231], v[0:3]
	v_mfma_f32_16x16x32_bf16 v[0:3], v[212:215], v[220:223], v[184:187]
	v_mfma_f32_16x16x32_bf16 v[32:35], v[216:219], v[228:231], v[0:3]
	v_mfma_f32_16x16x32_bf16 v[0:3], v[204:207], v[232:235], v[188:191]
	v_mfma_f32_16x16x32_bf16 v[20:23], v[208:211], v[236:239], v[0:3]
	v_mfma_f32_16x16x32_bf16 v[0:3], v[212:215], v[232:235], v[192:195]
	v_mfma_f32_16x16x32_bf16 v[16:19], v[216:219], v[236:239], v[0:3]
	v_mfma_f32_16x16x32_bf16 v[0:3], v[204:207], v[240:243], v[196:199]
	v_mfma_f32_16x16x32_bf16 v[4:7], v[208:211], v[244:247], v[0:3]
	v_mfma_f32_16x16x32_bf16 v[0:3], v[212:215], v[240:243], v[200:203]
	v_mfma_f32_16x16x32_bf16 v[0:3], v[216:219], v[244:247], v[0:3]
	s_setprio 0
	v_readlane_b32 s64, v254, 16
	v_readlane_b32 s65, v254, 17
	v_readlane_b32 s66, v254, 58
	v_readlane_b32 s67, v254, 59
	v_lshl_or_b32 v164, s96, 8, v152
	s_cmp_gt_i32 s96, 3
	s_cselect_b32 s64, s64, s66
	s_cselect_b32 s65, s65, s67
	v_and_b32_e32 v164, 0x3ff, v164
	v_mov_b32_e32 v165, 0
	v_lshl_add_u64 v[164:165], v[164:165], 2, s[64:65]
	global_load_dwordx4 v[166:169], v[164:165], off
	global_load_dwordx4 v[170:173], v[164:165], off offset:16
	global_load_dwordx4 v[174:177], v[164:165], off offset:512
	global_load_dwordx4 v[178:181], v[164:165], off offset:528
	s_barrier
	s_andn2_b64 vcc, exec, s[24:25]
	s_cbranch_vccnz .LBB0_332
	s_barrier
.LBB0_332:
	s_waitcnt vmcnt(0)
	v_lshl_add_u32 v144, s10, 8, v150
	v_ashrrev_i32_e32 v145, 31, v144
	v_lshl_or_b32 v142, s96, 8, v152
	v_lshlrev_b64 v[146:147], 10, v[144:145]
	v_cmp_lt_i32_e64 s[8:9], s33, v142
	v_add_u32_e32 v136, 0xfffffc00, v142
	v_lshl_add_u64 v[146:147], s[80:81], 0, v[146:147]
	s_and_saveexec_b64 s[0:1], s[8:9]
	s_xor_b64 s[10:11], exec, s[0:1]
	s_cbranch_execz .LBB0_334
	v_pk_add_f32 v[120:121], v[120:121], v[170:171]
	v_pk_add_f32 v[124:125], v[124:125], v[166:167]
	v_pk_add_f32 v[148:149], v[122:123], v[172:173]
	v_mul_f32_e32 v122, 0xbfb8aa3b, v124
	v_mul_f32_e32 v120, 0xbfb8aa3b, v120
	v_exp_f32_e32 v124, v122
	v_mul_f32_e32 v122, 0xbfb8aa3b, v125
	v_exp_f32_e32 v125, v120
	v_pk_add_f32 v[126:127], v[126:127], v[168:169]
	v_mul_f32_e32 v120, 0xbfb8aa3b, v121
	v_exp_f32_e32 v156, v122
	v_mul_f32_e32 v122, 0xbfb8aa3b, v126
	v_exp_f32_e32 v157, v120
	v_mul_f32_e32 v120, 0xbfb8aa3b, v148
	v_exp_f32_e32 v126, v122
	v_mul_f32_e32 v122, 0xbfb8aa3b, v127
	v_exp_f32_e32 v127, v120
	v_mul_f32_e32 v120, 0xbfb8aa3b, v149
	v_exp_f32_e32 v123, v120
	v_pk_add_f32 v[120:121], v[124:125], 1.0 op_sel_hi:[1,0]
	v_pk_add_f32 v[126:127], v[126:127], 1.0 op_sel_hi:[1,0]
	v_exp_f32_e32 v122, v122
	v_rcp_f32_e32 v121, v121
	v_pk_add_f32 v[122:123], v[122:123], 1.0 op_sel_hi:[1,0]
	v_rcp_f32_e32 v120, v120
	v_pk_add_f32 v[124:125], v[156:157], 1.0 op_sel_hi:[1,0]
	v_pk_fma_f32 v[120:121], v[120:121], s[28:29], 0.5 op_sel_hi:[1,0,0]
	v_rcp_f32_e32 v125, v125
	v_rcp_f32_e32 v124, v124
	v_rcp_f32_e32 v127, v127
	v_rcp_f32_e32 v126, v126
	v_rcp_f32_e32 v123, v123
	v_rcp_f32_e32 v122, v122
	v_cvt_u32_f32_e32 v143, v121
	v_cvt_u32_f32_e32 v148, v120
	v_pk_fma_f32 v[120:121], v[124:125], s[28:29], 0.5 op_sel_hi:[1,0,0]
	s_nop 0
	v_cvt_u32_f32_e32 v120, v120
	v_cvt_u32_f32_e32 v121, v121
	v_lshlrev_b32_e32 v120, 8, v120
	v_lshlrev_b32_e32 v121, 8, v121
	v_or_b32_e32 v124, v121, v143
	v_or_b32_e32 v125, v120, v148
	v_pk_fma_f32 v[120:121], v[126:127], s[28:29], 0.5 op_sel_hi:[1,0,0]
	s_nop 0
	v_cvt_u32_f32_sdwa v120, v120 dst_sel:WORD_1 dst_unused:UNUSED_PAD src0_sel:DWORD
	v_cvt_u32_f32_sdwa v121, v121 dst_sel:WORD_1 dst_unused:UNUSED_PAD src0_sel:DWORD
	v_or_b32_e32 v125, v125, v120
	v_or_b32_e32 v124, v124, v121
	v_pk_fma_f32 v[120:121], v[122:123], s[28:29], 0.5 op_sel_hi:[1,0,0]
	v_lshl_add_u64 v[122:123], v[146:147], 0, v[136:137]
	v_cvt_u32_f32_sdwa v120, v120 dst_sel:BYTE_3 dst_unused:UNUSED_PAD src0_sel:DWORD
	v_cvt_u32_f32_sdwa v121, v121 dst_sel:BYTE_3 dst_unused:UNUSED_PAD src0_sel:DWORD
	v_or_b32_e32 v120, v125, v120
	v_or_b32_e32 v121, v124, v121
	global_store_dwordx2 v[122:123], v[120:121], off
.LBB0_334:
	s_or_saveexec_b64 s[10:11], s[10:11]
	v_lshlrev_b64 v[148:149], 11, v[144:145]
	v_ashrrev_i32_e32 v143, 31, v142
	v_lshl_add_u64 v[148:149], s[62:63], 0, v[148:149]
	s_xor_b64 exec, exec, s[10:11]
	s_cbranch_execz .LBB0_336
	v_pk_add_f32 v[120:121], v[120:121], v[170:171]
	v_pk_add_f32 v[124:125], v[124:125], v[166:167]
	v_pk_add_f32 v[122:123], v[122:123], v[172:173]
	v_mul_f32_e32 v124, 0xbfb8aa3b, v124
	v_exp_f32_e32 v124, v124
	v_mul_f32_e32 v125, 0xbfb8aa3b, v125
	v_exp_f32_e32 v125, v125
	v_pk_add_f32 v[126:127], v[126:127], v[168:169]
	v_add_f32_e32 v124, 1.0, v124
	v_add_f32_e32 v125, 1.0, v125
	v_mul_f32_e32 v126, 0xbfb8aa3b, v126
	v_exp_f32_e32 v126, v126
	v_rcp_f32_e32 v124, v124
	v_add_f32_e32 v126, 1.0, v126
	v_mul_f32_e32 v127, 0xbfb8aa3b, v127
	v_exp_f32_e32 v127, v127
	v_rcp_f32_e32 v125, v125
	v_add_f32_e32 v127, 1.0, v127
	v_mul_f32_e32 v120, 0xbfb8aa3b, v120
	v_exp_f32_e32 v120, v120
	v_rcp_f32_e32 v126, v126
	v_add_f32_e32 v120, 1.0, v120
	v_mul_f32_e32 v124, 0xbf60028a, v124
	v_mul_f32_e32 v125, 0xbf60028a, v125
	v_rcp_f32_e32 v127, v127
	v_mul_f32_e32 v126, 0xbf60028a, v126
	v_mul_f32_e32 v127, 0xbf60028a, v127
	v_rcp_f32_e32 v120, v120
	s_nop 0
	v_mul_f32_e32 v145, 0xbf60028a, v120
	v_mul_f32_e32 v120, 0xbfb8aa3b, v121
	v_exp_f32_e32 v120, v120
	s_nop 0
	v_add_f32_e32 v120, 1.0, v120
	v_rcp_f32_e32 v120, v120
	s_nop 0
	v_mul_f32_e32 v158, 0xbf60028a, v120
	v_mul_f32_e32 v120, 0xbfb8aa3b, v122
	v_exp_f32_e32 v120, v120
	s_nop 0
	v_add_f32_e32 v120, 1.0, v120
	v_rcp_f32_e32 v120, v120
	s_nop 0
	v_mul_f32_e32 v159, 0xbf60028a, v120
	v_mul_f32_e32 v120, 0xbfb8aa3b, v123
	v_exp_f32_e32 v120, v120
	s_nop 0
	v_add_f32_e32 v120, 1.0, v120
	v_rcp_f32_e32 v120, v120
	s_nop 0
	v_mul_f32_e32 v123, 0xbf60028a, v120
	v_lshl_add_u64 v[156:157], v[142:143], 1, v[148:149]
	v_cvt_pk_bf16_f32 v120, v124, v125
	v_cvt_pk_bf16_f32 v121, v126, v127
	v_cvt_pk_bf16_f32 v122, v145, v158
	v_cvt_pk_bf16_f32 v123, v159, v123
	global_store_dwordx4 v[156:157], v[120:123], off
.LBB0_336:
	s_or_b64 exec, exec, s[10:11]
	s_nop 0
	v_or_b32_e32 v120, 0x80, v142
	v_cmp_lt_i32_e64 s[10:11], s33, v120
	v_add_u32_e32 v120, 0xfffffc80, v142
	s_and_saveexec_b64 s[0:1], s[10:11]
	s_xor_b64 s[96:97], exec, s[0:1]
	s_cbranch_execz .LBB0_338
	v_mov_b32_e32 v121, v137
	v_pk_add_f32 v[112:113], v[112:113], v[178:179]
	v_pk_add_f32 v[116:117], v[116:117], v[174:175]
	v_pk_add_f32 v[124:125], v[114:115], v[180:181]
	v_mul_f32_e32 v114, 0xbfb8aa3b, v116
	v_mul_f32_e32 v112, 0xbfb8aa3b, v112
	v_exp_f32_e32 v116, v114
	v_mul_f32_e32 v114, 0xbfb8aa3b, v117
	v_exp_f32_e32 v117, v112
	v_pk_add_f32 v[118:119], v[118:119], v[176:177]
	v_mul_f32_e32 v112, 0xbfb8aa3b, v113
	v_exp_f32_e32 v122, v114
	v_mul_f32_e32 v114, 0xbfb8aa3b, v118
	v_exp_f32_e32 v123, v112
	v_mul_f32_e32 v112, 0xbfb8aa3b, v124
	v_exp_f32_e32 v118, v114
	v_mul_f32_e32 v114, 0xbfb8aa3b, v119
	v_exp_f32_e32 v119, v112
	v_mul_f32_e32 v112, 0xbfb8aa3b, v125
	v_exp_f32_e32 v115, v112
	v_pk_add_f32 v[112:113], v[116:117], 1.0 op_sel_hi:[1,0]
	v_pk_add_f32 v[118:119], v[118:119], 1.0 op_sel_hi:[1,0]
	v_exp_f32_e32 v114, v114
	v_rcp_f32_e32 v113, v113
	v_pk_add_f32 v[114:115], v[114:115], 1.0 op_sel_hi:[1,0]
	v_rcp_f32_e32 v112, v112
	v_pk_add_f32 v[116:117], v[122:123], 1.0 op_sel_hi:[1,0]
	v_pk_fma_f32 v[112:113], v[112:113], s[28:29], 0.5 op_sel_hi:[1,0,0]
	v_rcp_f32_e32 v117, v117
	v_rcp_f32_e32 v116, v116
	v_rcp_f32_e32 v119, v119
	v_rcp_f32_e32 v118, v118
	v_rcp_f32_e32 v115, v115
	v_rcp_f32_e32 v114, v114
	v_cvt_u32_f32_e32 v122, v113
	v_cvt_u32_f32_e32 v123, v112
	v_pk_fma_f32 v[112:113], v[116:117], s[28:29], 0.5 op_sel_hi:[1,0,0]
	s_nop 0
	v_cvt_u32_f32_e32 v112, v112
	v_cvt_u32_f32_e32 v113, v113
	v_lshlrev_b32_e32 v112, 8, v112
	v_lshlrev_b32_e32 v113, 8, v113
	v_or_b32_e32 v116, v113, v122
	v_or_b32_e32 v117, v112, v123
	v_pk_fma_f32 v[112:113], v[118:119], s[28:29], 0.5 op_sel_hi:[1,0,0]
	s_nop 0
	v_cvt_u32_f32_sdwa v112, v112 dst_sel:WORD_1 dst_unused:UNUSED_PAD src0_sel:DWORD
	v_cvt_u32_f32_sdwa v113, v113 dst_sel:WORD_1 dst_unused:UNUSED_PAD src0_sel:DWORD
	v_or_b32_e32 v117, v117, v112
	v_or_b32_e32 v116, v116, v113
	v_pk_fma_f32 v[112:113], v[114:115], s[28:29], 0.5 op_sel_hi:[1,0,0]
	v_lshl_add_u64 v[114:115], v[146:147], 0, v[120:121]
	v_cvt_u32_f32_sdwa v112, v112 dst_sel:BYTE_3 dst_unused:UNUSED_PAD src0_sel:DWORD
	v_cvt_u32_f32_sdwa v113, v113 dst_sel:BYTE_3 dst_unused:UNUSED_PAD src0_sel:DWORD
	v_or_b32_e32 v112, v117, v112
	v_or_b32_e32 v113, v116, v113
	global_store_dwordx2 v[114:115], v[112:113], off
.LBB0_338:
	s_andn2_saveexec_b64 s[96:97], s[96:97]
	s_cbranch_execz .LBB0_340
	v_pk_add_f32 v[112:113], v[112:113], v[178:179]
	v_pk_add_f32 v[116:117], v[116:117], v[174:175]
	v_pk_add_f32 v[114:115], v[114:115], v[180:181]
	v_mul_f32_e32 v116, 0xbfb8aa3b, v116
	v_exp_f32_e32 v116, v116
	v_mul_f32_e32 v117, 0xbfb8aa3b, v117
	v_exp_f32_e32 v117, v117
	v_pk_add_f32 v[118:119], v[118:119], v[176:177]
	v_add_f32_e32 v116, 1.0, v116
	v_add_f32_e32 v117, 1.0, v117
	v_mul_f32_e32 v118, 0xbfb8aa3b, v118
	v_exp_f32_e32 v118, v118
	v_rcp_f32_e32 v116, v116
	v_add_f32_e32 v118, 1.0, v118
	v_mul_f32_e32 v119, 0xbfb8aa3b, v119
	v_exp_f32_e32 v119, v119
	v_rcp_f32_e32 v117, v117
	v_add_f32_e32 v119, 1.0, v119
	v_mul_f32_e32 v112, 0xbfb8aa3b, v112
	v_exp_f32_e32 v112, v112
	v_rcp_f32_e32 v118, v118
	v_add_f32_e32 v112, 1.0, v112
	v_mul_f32_e32 v116, 0xbf60028a, v116
	v_mul_f32_e32 v117, 0xbf60028a, v117
	v_rcp_f32_e32 v119, v119
	v_mul_f32_e32 v118, 0xbf60028a, v118
	v_mul_f32_e32 v119, 0xbf60028a, v119
	v_rcp_f32_e32 v112, v112
	s_nop 0
	v_mul_f32_e32 v121, 0xbf60028a, v112
	v_mul_f32_e32 v112, 0xbfb8aa3b, v113
	v_exp_f32_e32 v112, v112
	s_nop 0
	v_add_f32_e32 v112, 1.0, v112
	v_rcp_f32_e32 v112, v112
	s_nop 0
	v_mul_f32_e32 v124, 0xbf60028a, v112
	v_mul_f32_e32 v112, 0xbfb8aa3b, v114
	v_exp_f32_e32 v112, v112
	s_nop 0
	v_add_f32_e32 v112, 1.0, v112
	v_rcp_f32_e32 v112, v112
	s_nop 0
	v_mul_f32_e32 v125, 0xbf60028a, v112
	v_mul_f32_e32 v112, 0xbfb8aa3b, v115
	v_exp_f32_e32 v112, v112
	s_nop 0
	v_add_f32_e32 v112, 1.0, v112
	v_rcp_f32_e32 v112, v112
	s_nop 0
	v_mul_f32_e32 v115, 0xbf60028a, v112
	v_lshl_add_u64 v[122:123], v[142:143], 1, v[148:149]
	v_cvt_pk_bf16_f32 v112, v116, v117
	v_cvt_pk_bf16_f32 v113, v118, v119
	v_cvt_pk_bf16_f32 v114, v121, v124
	v_cvt_pk_bf16_f32 v115, v125, v115
	global_store_dwordx4 v[122:123], v[112:115], off offset:256
.LBB0_340:
	s_or_b64 exec, exec, s[96:97]
	s_nop 0
	v_or_b32_e32 v114, 16, v144
	v_ashrrev_i32_e32 v115, 31, v114
	v_lshlrev_b64 v[112:113], 10, v[114:115]
	v_lshl_add_u64 v[112:113], s[80:81], 0, v[112:113]
	s_and_saveexec_b64 s[0:1], s[8:9]
	s_xor_b64 s[96:97], exec, s[0:1]
	s_cbranch_execz .LBB0_342
	v_pk_add_f32 v[104:105], v[104:105], v[170:171]
	v_pk_add_f32 v[108:109], v[108:109], v[166:167]
	v_pk_add_f32 v[118:119], v[106:107], v[172:173]
	v_mul_f32_e32 v106, 0xbfb8aa3b, v108
	v_mul_f32_e32 v104, 0xbfb8aa3b, v104
	v_exp_f32_e32 v108, v106
	v_mul_f32_e32 v106, 0xbfb8aa3b, v109
	v_exp_f32_e32 v109, v104
	v_pk_add_f32 v[110:111], v[110:111], v[168:169]
	v_mul_f32_e32 v104, 0xbfb8aa3b, v105
	v_exp_f32_e32 v116, v106
	v_mul_f32_e32 v106, 0xbfb8aa3b, v110
	v_exp_f32_e32 v117, v104
	v_mul_f32_e32 v104, 0xbfb8aa3b, v118
	v_exp_f32_e32 v110, v106
	v_mul_f32_e32 v106, 0xbfb8aa3b, v111
	v_exp_f32_e32 v111, v104
	v_mul_f32_e32 v104, 0xbfb8aa3b, v119
	v_exp_f32_e32 v107, v104
	v_pk_add_f32 v[104:105], v[108:109], 1.0 op_sel_hi:[1,0]
	v_pk_add_f32 v[110:111], v[110:111], 1.0 op_sel_hi:[1,0]
	v_exp_f32_e32 v106, v106
	v_rcp_f32_e32 v105, v105
	v_pk_add_f32 v[106:107], v[106:107], 1.0 op_sel_hi:[1,0]
	v_rcp_f32_e32 v104, v104
	v_pk_add_f32 v[108:109], v[116:117], 1.0 op_sel_hi:[1,0]
	v_pk_fma_f32 v[104:105], v[104:105], s[28:29], 0.5 op_sel_hi:[1,0,0]
	v_rcp_f32_e32 v109, v109
	v_rcp_f32_e32 v108, v108
	v_rcp_f32_e32 v111, v111
	v_rcp_f32_e32 v110, v110
	v_rcp_f32_e32 v107, v107
	v_rcp_f32_e32 v106, v106
	v_cvt_u32_f32_e32 v116, v105
	v_cvt_u32_f32_e32 v117, v104
	v_pk_fma_f32 v[104:105], v[108:109], s[28:29], 0.5 op_sel_hi:[1,0,0]
	s_nop 0
	v_cvt_u32_f32_e32 v104, v104
	v_cvt_u32_f32_e32 v105, v105
	v_lshlrev_b32_e32 v104, 8, v104
	v_lshlrev_b32_e32 v105, 8, v105
	v_or_b32_e32 v108, v105, v116
	v_or_b32_e32 v109, v104, v117
	v_pk_fma_f32 v[104:105], v[110:111], s[28:29], 0.5 op_sel_hi:[1,0,0]
	s_nop 0
	v_cvt_u32_f32_sdwa v104, v104 dst_sel:WORD_1 dst_unused:UNUSED_PAD src0_sel:DWORD
	v_cvt_u32_f32_sdwa v105, v105 dst_sel:WORD_1 dst_unused:UNUSED_PAD src0_sel:DWORD
	v_or_b32_e32 v109, v109, v104
	v_or_b32_e32 v108, v108, v105
	v_pk_fma_f32 v[104:105], v[106:107], s[28:29], 0.5 op_sel_hi:[1,0,0]
	v_lshl_add_u64 v[106:107], v[112:113], 0, v[136:137]
	v_cvt_u32_f32_sdwa v104, v104 dst_sel:BYTE_3 dst_unused:UNUSED_PAD src0_sel:DWORD
	v_cvt_u32_f32_sdwa v105, v105 dst_sel:BYTE_3 dst_unused:UNUSED_PAD src0_sel:DWORD
	v_or_b32_e32 v104, v109, v104
	v_or_b32_e32 v105, v108, v105
	global_store_dwordx2 v[106:107], v[104:105], off

.LBB0_345:
	v_pk_add_f32 v[96:97], v[96:97], v[178:179]
	v_pk_add_f32 v[100:101], v[100:101], v[174:175]
	v_pk_add_f32 v[98:99], v[98:99], v[180:181]
	v_mul_f32_e32 v100, 0xbfb8aa3b, v100
	v_exp_f32_e32 v100, v100
	v_mul_f32_e32 v101, 0xbfb8aa3b, v101
	v_exp_f32_e32 v101, v101
	v_pk_add_f32 v[102:103], v[102:103], v[176:177]
	v_add_f32_e32 v100, 1.0, v100
	v_add_f32_e32 v101, 1.0, v101
	v_mul_f32_e32 v102, 0xbfb8aa3b, v102
	v_exp_f32_e32 v102, v102
	v_rcp_f32_e32 v100, v100
	v_add_f32_e32 v102, 1.0, v102
	v_mul_f32_e32 v103, 0xbfb8aa3b, v103
	v_exp_f32_e32 v103, v103
	v_rcp_f32_e32 v101, v101
	v_add_f32_e32 v103, 1.0, v103
	v_mul_f32_e32 v96, 0xbfb8aa3b, v96
	v_exp_f32_e32 v96, v96
	v_rcp_f32_e32 v102, v102
	v_add_f32_e32 v96, 1.0, v96
	v_mul_f32_e32 v100, 0xbf60028a, v100
	v_mul_f32_e32 v101, 0xbf60028a, v101
	v_rcp_f32_e32 v103, v103
	v_mul_f32_e32 v102, 0xbf60028a, v102
	v_mul_f32_e32 v103, 0xbf60028a, v103
	v_rcp_f32_e32 v96, v96
	s_nop 0
	v_mul_f32_e32 v106, 0xbf60028a, v96
	v_mul_f32_e32 v96, 0xbfb8aa3b, v97
	v_exp_f32_e32 v96, v96
	s_nop 0
	v_add_f32_e32 v96, 1.0, v96
	v_rcp_f32_e32 v96, v96
	s_nop 0
	v_mul_f32_e32 v107, 0xbf60028a, v96
	v_mul_f32_e32 v96, 0xbfb8aa3b, v98
	v_exp_f32_e32 v96, v96
	s_nop 0
	v_add_f32_e32 v96, 1.0, v96
	v_rcp_f32_e32 v96, v96
	s_nop 0
	v_mul_f32_e32 v108, 0xbf60028a, v96
	v_mul_f32_e32 v96, 0xbfb8aa3b, v99
	v_exp_f32_e32 v96, v96
	s_nop 0
	v_add_f32_e32 v96, 1.0, v96
	v_rcp_f32_e32 v96, v96
	s_nop 0
	v_mul_f32_e32 v99, 0xbf60028a, v96
	v_lshl_add_u64 v[104:105], v[142:143], 1, v[114:115]
	v_cvt_pk_bf16_f32 v96, v100, v101
	v_cvt_pk_bf16_f32 v97, v102, v103
	v_cvt_pk_bf16_f32 v98, v106, v107
	v_cvt_pk_bf16_f32 v99, v108, v99
	global_store_dwordx4 v[104:105], v[96:99], off offset:256
.LBB0_346:
	s_or_b64 exec, exec, s[96:97]
	s_nop 0
	v_or_b32_e32 v98, 32, v144
	v_ashrrev_i32_e32 v99, 31, v98
	v_lshlrev_b64 v[96:97], 10, v[98:99]
	v_lshl_add_u64 v[96:97], s[80:81], 0, v[96:97]
	s_and_saveexec_b64 s[0:1], s[8:9]
	s_xor_b64 s[96:97], exec, s[0:1]
	s_cbranch_execz .LBB0_348
	v_pk_add_f32 v[88:89], v[88:89], v[170:171]
	v_pk_add_f32 v[92:93], v[92:93], v[166:167]
	v_pk_add_f32 v[102:103], v[90:91], v[172:173]
	v_mul_f32_e32 v90, 0xbfb8aa3b, v92
	v_mul_f32_e32 v88, 0xbfb8aa3b, v88
	v_exp_f32_e32 v92, v90
	v_mul_f32_e32 v90, 0xbfb8aa3b, v93
	v_exp_f32_e32 v93, v88
	v_pk_add_f32 v[94:95], v[94:95], v[168:169]
	v_mul_f32_e32 v88, 0xbfb8aa3b, v89
	v_exp_f32_e32 v100, v90
	v_mul_f32_e32 v90, 0xbfb8aa3b, v94
	v_exp_f32_e32 v101, v88
	v_mul_f32_e32 v88, 0xbfb8aa3b, v102
	v_exp_f32_e32 v94, v90
	v_mul_f32_e32 v90, 0xbfb8aa3b, v95
	v_exp_f32_e32 v95, v88
	v_mul_f32_e32 v88, 0xbfb8aa3b, v103
	v_exp_f32_e32 v91, v88
	v_pk_add_f32 v[88:89], v[92:93], 1.0 op_sel_hi:[1,0]
	v_pk_add_f32 v[94:95], v[94:95], 1.0 op_sel_hi:[1,0]
	v_exp_f32_e32 v90, v90
	v_rcp_f32_e32 v89, v89
	v_pk_add_f32 v[90:91], v[90:91], 1.0 op_sel_hi:[1,0]
	v_rcp_f32_e32 v88, v88
	v_pk_add_f32 v[92:93], v[100:101], 1.0 op_sel_hi:[1,0]
	v_pk_fma_f32 v[88:89], v[88:89], s[28:29], 0.5 op_sel_hi:[1,0,0]
	v_rcp_f32_e32 v93, v93
	v_rcp_f32_e32 v92, v92
	v_rcp_f32_e32 v95, v95
	v_rcp_f32_e32 v94, v94
	v_rcp_f32_e32 v91, v91
	v_rcp_f32_e32 v90, v90
	v_cvt_u32_f32_e32 v100, v89
	v_cvt_u32_f32_e32 v101, v88
	v_pk_fma_f32 v[88:89], v[92:93], s[28:29], 0.5 op_sel_hi:[1,0,0]
	s_nop 0
	v_cvt_u32_f32_e32 v88, v88
	v_cvt_u32_f32_e32 v89, v89
	v_lshlrev_b32_e32 v88, 8, v88
	v_lshlrev_b32_e32 v89, 8, v89
	v_or_b32_e32 v92, v89, v100
	v_or_b32_e32 v93, v88, v101
	v_pk_fma_f32 v[88:89], v[94:95], s[28:29], 0.5 op_sel_hi:[1,0,0]
	s_nop 0
	v_cvt_u32_f32_sdwa v88, v88 dst_sel:WORD_1 dst_unused:UNUSED_PAD src0_sel:DWORD
	v_cvt_u32_f32_sdwa v89, v89 dst_sel:WORD_1 dst_unused:UNUSED_PAD src0_sel:DWORD
	v_or_b32_e32 v93, v93, v88
	v_or_b32_e32 v92, v92, v89
	v_pk_fma_f32 v[88:89], v[90:91], s[28:29], 0.5 op_sel_hi:[1,0,0]
	v_lshl_add_u64 v[90:91], v[96:97], 0, v[136:137]
	v_cvt_u32_f32_sdwa v88, v88 dst_sel:BYTE_3 dst_unused:UNUSED_PAD src0_sel:DWORD
	v_cvt_u32_f32_sdwa v89, v89 dst_sel:BYTE_3 dst_unused:UNUSED_PAD src0_sel:DWORD
	v_or_b32_e32 v88, v93, v88
	v_or_b32_e32 v89, v92, v89
	global_store_dwordx2 v[90:91], v[88:89], off

.LBB0_351:
	v_pk_add_f32 v[80:81], v[80:81], v[178:179]
	v_pk_add_f32 v[84:85], v[84:85], v[174:175]
	v_pk_add_f32 v[82:83], v[82:83], v[180:181]
	v_mul_f32_e32 v84, 0xbfb8aa3b, v84
	v_exp_f32_e32 v84, v84
	v_mul_f32_e32 v85, 0xbfb8aa3b, v85
	v_exp_f32_e32 v85, v85
	v_pk_add_f32 v[86:87], v[86:87], v[176:177]
	v_add_f32_e32 v84, 1.0, v84
	v_add_f32_e32 v85, 1.0, v85
	v_mul_f32_e32 v86, 0xbfb8aa3b, v86
	v_exp_f32_e32 v86, v86
	v_rcp_f32_e32 v84, v84
	v_add_f32_e32 v86, 1.0, v86
	v_mul_f32_e32 v87, 0xbfb8aa3b, v87
	v_exp_f32_e32 v87, v87
	v_rcp_f32_e32 v85, v85
	v_add_f32_e32 v87, 1.0, v87
	v_mul_f32_e32 v80, 0xbfb8aa3b, v80
	v_exp_f32_e32 v80, v80
	v_rcp_f32_e32 v86, v86
	v_add_f32_e32 v80, 1.0, v80
	v_mul_f32_e32 v84, 0xbf60028a, v84
	v_mul_f32_e32 v85, 0xbf60028a, v85
	v_rcp_f32_e32 v87, v87
	v_mul_f32_e32 v86, 0xbf60028a, v86
	v_mul_f32_e32 v87, 0xbf60028a, v87
	v_rcp_f32_e32 v80, v80
	s_nop 0
	v_mul_f32_e32 v90, 0xbf60028a, v80
	v_mul_f32_e32 v80, 0xbfb8aa3b, v81
	v_exp_f32_e32 v80, v80
	s_nop 0
	v_add_f32_e32 v80, 1.0, v80
	v_rcp_f32_e32 v80, v80
	s_nop 0
	v_mul_f32_e32 v91, 0xbf60028a, v80
	v_mul_f32_e32 v80, 0xbfb8aa3b, v82
	v_exp_f32_e32 v80, v80
	s_nop 0
	v_add_f32_e32 v80, 1.0, v80
	v_rcp_f32_e32 v80, v80
	s_nop 0
	v_mul_f32_e32 v92, 0xbf60028a, v80
	v_mul_f32_e32 v80, 0xbfb8aa3b, v83
	v_exp_f32_e32 v80, v80
	s_nop 0
	v_add_f32_e32 v80, 1.0, v80
	v_rcp_f32_e32 v80, v80
	s_nop 0
	v_mul_f32_e32 v83, 0xbf60028a, v80
	v_lshl_add_u64 v[88:89], v[142:143], 1, v[98:99]
	v_cvt_pk_bf16_f32 v80, v84, v85
	v_cvt_pk_bf16_f32 v81, v86, v87
	v_cvt_pk_bf16_f32 v82, v90, v91
	v_cvt_pk_bf16_f32 v83, v92, v83
	global_store_dwordx4 v[88:89], v[80:83], off offset:256
.LBB0_352:
	s_or_b64 exec, exec, s[96:97]
	s_nop 0
	v_or_b32_e32 v82, 48, v144
	v_ashrrev_i32_e32 v83, 31, v82
	v_lshlrev_b64 v[80:81], 10, v[82:83]
	v_lshl_add_u64 v[80:81], s[80:81], 0, v[80:81]
	s_and_saveexec_b64 s[0:1], s[8:9]
	s_xor_b64 s[96:97], exec, s[0:1]
	s_cbranch_execz .LBB0_354
	v_pk_add_f32 v[72:73], v[72:73], v[170:171]
	v_pk_add_f32 v[76:77], v[76:77], v[166:167]
	v_pk_add_f32 v[86:87], v[74:75], v[172:173]
	v_mul_f32_e32 v74, 0xbfb8aa3b, v76
	v_mul_f32_e32 v72, 0xbfb8aa3b, v72
	v_exp_f32_e32 v76, v74
	v_mul_f32_e32 v74, 0xbfb8aa3b, v77
	v_exp_f32_e32 v77, v72
	v_pk_add_f32 v[78:79], v[78:79], v[168:169]
	v_mul_f32_e32 v72, 0xbfb8aa3b, v73
	v_exp_f32_e32 v84, v74
	v_mul_f32_e32 v74, 0xbfb8aa3b, v78
	v_exp_f32_e32 v85, v72
	v_mul_f32_e32 v72, 0xbfb8aa3b, v86
	v_exp_f32_e32 v78, v74
	v_mul_f32_e32 v74, 0xbfb8aa3b, v79
	v_exp_f32_e32 v79, v72
	v_mul_f32_e32 v72, 0xbfb8aa3b, v87
	v_exp_f32_e32 v75, v72
	v_pk_add_f32 v[72:73], v[76:77], 1.0 op_sel_hi:[1,0]
	v_pk_add_f32 v[78:79], v[78:79], 1.0 op_sel_hi:[1,0]
	v_exp_f32_e32 v74, v74
	v_rcp_f32_e32 v73, v73
	v_pk_add_f32 v[74:75], v[74:75], 1.0 op_sel_hi:[1,0]
	v_rcp_f32_e32 v72, v72
	v_pk_add_f32 v[76:77], v[84:85], 1.0 op_sel_hi:[1,0]
	v_pk_fma_f32 v[72:73], v[72:73], s[28:29], 0.5 op_sel_hi:[1,0,0]
	v_rcp_f32_e32 v77, v77
	v_rcp_f32_e32 v76, v76
	v_rcp_f32_e32 v79, v79
	v_rcp_f32_e32 v78, v78
	v_rcp_f32_e32 v75, v75
	v_rcp_f32_e32 v74, v74
	v_cvt_u32_f32_e32 v84, v73
	v_cvt_u32_f32_e32 v85, v72
	v_pk_fma_f32 v[72:73], v[76:77], s[28:29], 0.5 op_sel_hi:[1,0,0]
	s_nop 0
	v_cvt_u32_f32_e32 v72, v72
	v_cvt_u32_f32_e32 v73, v73
	v_lshlrev_b32_e32 v72, 8, v72
	v_lshlrev_b32_e32 v73, 8, v73
	v_or_b32_e32 v76, v73, v84
	v_or_b32_e32 v77, v72, v85
	v_pk_fma_f32 v[72:73], v[78:79], s[28:29], 0.5 op_sel_hi:[1,0,0]
	s_nop 0
	v_cvt_u32_f32_sdwa v72, v72 dst_sel:WORD_1 dst_unused:UNUSED_PAD src0_sel:DWORD
	v_cvt_u32_f32_sdwa v73, v73 dst_sel:WORD_1 dst_unused:UNUSED_PAD src0_sel:DWORD
	v_or_b32_e32 v77, v77, v72
	v_or_b32_e32 v76, v76, v73
	v_pk_fma_f32 v[72:73], v[74:75], s[28:29], 0.5 op_sel_hi:[1,0,0]
	v_lshl_add_u64 v[74:75], v[80:81], 0, v[136:137]
	v_cvt_u32_f32_sdwa v72, v72 dst_sel:BYTE_3 dst_unused:UNUSED_PAD src0_sel:DWORD
	v_cvt_u32_f32_sdwa v73, v73 dst_sel:BYTE_3 dst_unused:UNUSED_PAD src0_sel:DWORD
	v_or_b32_e32 v72, v77, v72
	v_or_b32_e32 v73, v76, v73
	global_store_dwordx2 v[74:75], v[72:73], off

.LBB0_357:
	v_pk_add_f32 v[64:65], v[64:65], v[178:179]
	v_pk_add_f32 v[68:69], v[68:69], v[174:175]
	v_pk_add_f32 v[66:67], v[66:67], v[180:181]
	v_mul_f32_e32 v68, 0xbfb8aa3b, v68
	v_exp_f32_e32 v68, v68
	v_mul_f32_e32 v69, 0xbfb8aa3b, v69
	v_exp_f32_e32 v69, v69
	v_pk_add_f32 v[70:71], v[70:71], v[176:177]
	v_add_f32_e32 v68, 1.0, v68
	v_add_f32_e32 v69, 1.0, v69
	v_mul_f32_e32 v70, 0xbfb8aa3b, v70
	v_exp_f32_e32 v70, v70
	v_rcp_f32_e32 v68, v68
	v_add_f32_e32 v70, 1.0, v70
	v_mul_f32_e32 v71, 0xbfb8aa3b, v71
	v_exp_f32_e32 v71, v71
	v_rcp_f32_e32 v69, v69
	v_add_f32_e32 v71, 1.0, v71
	v_mul_f32_e32 v64, 0xbfb8aa3b, v64
	v_exp_f32_e32 v64, v64
	v_rcp_f32_e32 v70, v70
	v_add_f32_e32 v64, 1.0, v64
	v_mul_f32_e32 v68, 0xbf60028a, v68
	v_mul_f32_e32 v69, 0xbf60028a, v69
	v_rcp_f32_e32 v71, v71
	v_mul_f32_e32 v70, 0xbf60028a, v70
	v_mul_f32_e32 v71, 0xbf60028a, v71
	v_rcp_f32_e32 v64, v64
	s_nop 0
	v_mul_f32_e32 v74, 0xbf60028a, v64
	v_mul_f32_e32 v64, 0xbfb8aa3b, v65
	v_exp_f32_e32 v64, v64
	s_nop 0
	v_add_f32_e32 v64, 1.0, v64
	v_rcp_f32_e32 v64, v64
	s_nop 0
	v_mul_f32_e32 v75, 0xbf60028a, v64
	v_mul_f32_e32 v64, 0xbfb8aa3b, v66
	v_exp_f32_e32 v64, v64
	s_nop 0
	v_add_f32_e32 v64, 1.0, v64
	v_rcp_f32_e32 v64, v64
	s_nop 0
	v_mul_f32_e32 v76, 0xbf60028a, v64
	v_mul_f32_e32 v64, 0xbfb8aa3b, v67
	v_exp_f32_e32 v64, v64
	s_nop 0
	v_add_f32_e32 v64, 1.0, v64
	v_rcp_f32_e32 v64, v64
	s_nop 0
	v_mul_f32_e32 v67, 0xbf60028a, v64
	v_lshl_add_u64 v[72:73], v[142:143], 1, v[82:83]
	v_cvt_pk_bf16_f32 v64, v68, v69
	v_cvt_pk_bf16_f32 v65, v70, v71
	v_cvt_pk_bf16_f32 v66, v74, v75
	v_cvt_pk_bf16_f32 v67, v76, v67
	global_store_dwordx4 v[72:73], v[64:67], off offset:256
.LBB0_358:
	s_or_b64 exec, exec, s[96:97]
	s_nop 0
	v_add_u32_e32 v66, 0x80, v144
	v_ashrrev_i32_e32 v67, 31, v66
	v_lshlrev_b64 v[64:65], 10, v[66:67]
	v_lshl_add_u64 v[64:65], s[80:81], 0, v[64:65]
	s_and_saveexec_b64 s[0:1], s[8:9]
	s_xor_b64 s[96:97], exec, s[0:1]
	s_cbranch_execz .LBB0_360
	v_pk_add_f32 v[56:57], v[56:57], v[170:171]
	v_pk_add_f32 v[60:61], v[60:61], v[166:167]
	v_pk_add_f32 v[70:71], v[58:59], v[172:173]
	v_mul_f32_e32 v58, 0xbfb8aa3b, v60
	v_mul_f32_e32 v56, 0xbfb8aa3b, v56
	v_exp_f32_e32 v60, v58
	v_mul_f32_e32 v58, 0xbfb8aa3b, v61
	v_exp_f32_e32 v61, v56
	v_pk_add_f32 v[62:63], v[62:63], v[168:169]
	v_mul_f32_e32 v56, 0xbfb8aa3b, v57
	v_exp_f32_e32 v68, v58
	v_mul_f32_e32 v58, 0xbfb8aa3b, v62
	v_exp_f32_e32 v69, v56
	v_mul_f32_e32 v56, 0xbfb8aa3b, v70
	v_exp_f32_e32 v62, v58
	v_mul_f32_e32 v58, 0xbfb8aa3b, v63
	v_exp_f32_e32 v63, v56
	v_mul_f32_e32 v56, 0xbfb8aa3b, v71
	v_exp_f32_e32 v59, v56
	v_pk_add_f32 v[56:57], v[60:61], 1.0 op_sel_hi:[1,0]
	v_pk_add_f32 v[62:63], v[62:63], 1.0 op_sel_hi:[1,0]
	v_exp_f32_e32 v58, v58
	v_rcp_f32_e32 v57, v57
	v_pk_add_f32 v[58:59], v[58:59], 1.0 op_sel_hi:[1,0]
	v_rcp_f32_e32 v56, v56
	v_pk_add_f32 v[60:61], v[68:69], 1.0 op_sel_hi:[1,0]
	v_pk_fma_f32 v[56:57], v[56:57], s[28:29], 0.5 op_sel_hi:[1,0,0]
	v_rcp_f32_e32 v61, v61
	v_rcp_f32_e32 v60, v60
	v_rcp_f32_e32 v63, v63
	v_rcp_f32_e32 v62, v62
	v_rcp_f32_e32 v59, v59
	v_rcp_f32_e32 v58, v58
	v_cvt_u32_f32_e32 v68, v57
	v_cvt_u32_f32_e32 v69, v56
	v_pk_fma_f32 v[56:57], v[60:61], s[28:29], 0.5 op_sel_hi:[1,0,0]
	s_nop 0
	v_cvt_u32_f32_e32 v56, v56
	v_cvt_u32_f32_e32 v57, v57
	v_lshlrev_b32_e32 v56, 8, v56
	v_lshlrev_b32_e32 v57, 8, v57
	v_or_b32_e32 v60, v57, v68
	v_or_b32_e32 v61, v56, v69
	v_pk_fma_f32 v[56:57], v[62:63], s[28:29], 0.5 op_sel_hi:[1,0,0]
	s_nop 0
	v_cvt_u32_f32_sdwa v56, v56 dst_sel:WORD_1 dst_unused:UNUSED_PAD src0_sel:DWORD
	v_cvt_u32_f32_sdwa v57, v57 dst_sel:WORD_1 dst_unused:UNUSED_PAD src0_sel:DWORD
	v_or_b32_e32 v61, v61, v56
	v_or_b32_e32 v60, v60, v57
	v_pk_fma_f32 v[56:57], v[58:59], s[28:29], 0.5 op_sel_hi:[1,0,0]
	v_lshl_add_u64 v[58:59], v[64:65], 0, v[136:137]
	v_cvt_u32_f32_sdwa v56, v56 dst_sel:BYTE_3 dst_unused:UNUSED_PAD src0_sel:DWORD
	v_cvt_u32_f32_sdwa v57, v57 dst_sel:BYTE_3 dst_unused:UNUSED_PAD src0_sel:DWORD
	v_or_b32_e32 v56, v61, v56
	v_or_b32_e32 v57, v60, v57
	global_store_dwordx2 v[58:59], v[56:57], off

.LBB0_363:
	v_pk_add_f32 v[48:49], v[48:49], v[178:179]
	v_pk_add_f32 v[52:53], v[52:53], v[174:175]
	v_pk_add_f32 v[50:51], v[50:51], v[180:181]
	v_mul_f32_e32 v52, 0xbfb8aa3b, v52
	v_exp_f32_e32 v52, v52
	v_mul_f32_e32 v53, 0xbfb8aa3b, v53
	v_exp_f32_e32 v53, v53
	v_pk_add_f32 v[54:55], v[54:55], v[176:177]
	v_add_f32_e32 v52, 1.0, v52
	v_add_f32_e32 v53, 1.0, v53
	v_mul_f32_e32 v54, 0xbfb8aa3b, v54
	v_exp_f32_e32 v54, v54
	v_rcp_f32_e32 v52, v52
	v_add_f32_e32 v54, 1.0, v54
	v_mul_f32_e32 v55, 0xbfb8aa3b, v55
	v_exp_f32_e32 v55, v55
	v_rcp_f32_e32 v53, v53
	v_add_f32_e32 v55, 1.0, v55
	v_mul_f32_e32 v48, 0xbfb8aa3b, v48
	v_exp_f32_e32 v48, v48
	v_rcp_f32_e32 v54, v54
	v_add_f32_e32 v48, 1.0, v48
	v_mul_f32_e32 v52, 0xbf60028a, v52
	v_mul_f32_e32 v53, 0xbf60028a, v53
	v_rcp_f32_e32 v55, v55
	v_mul_f32_e32 v54, 0xbf60028a, v54
	v_mul_f32_e32 v55, 0xbf60028a, v55
	v_rcp_f32_e32 v48, v48
	s_nop 0
	v_mul_f32_e32 v58, 0xbf60028a, v48
	v_mul_f32_e32 v48, 0xbfb8aa3b, v49
	v_exp_f32_e32 v48, v48
	s_nop 0
	v_add_f32_e32 v48, 1.0, v48
	v_rcp_f32_e32 v48, v48
	s_nop 0
	v_mul_f32_e32 v59, 0xbf60028a, v48
	v_mul_f32_e32 v48, 0xbfb8aa3b, v50
	v_exp_f32_e32 v48, v48
	s_nop 0
	v_add_f32_e32 v48, 1.0, v48
	v_rcp_f32_e32 v48, v48
	s_nop 0
	v_mul_f32_e32 v60, 0xbf60028a, v48
	v_mul_f32_e32 v48, 0xbfb8aa3b, v51
	v_exp_f32_e32 v48, v48
	s_nop 0
	v_add_f32_e32 v48, 1.0, v48
	v_rcp_f32_e32 v48, v48
	s_nop 0
	v_mul_f32_e32 v51, 0xbf60028a, v48
	v_lshl_add_u64 v[56:57], v[142:143], 1, v[66:67]
	v_cvt_pk_bf16_f32 v48, v52, v53
	v_cvt_pk_bf16_f32 v49, v54, v55
	v_cvt_pk_bf16_f32 v50, v58, v59
	v_cvt_pk_bf16_f32 v51, v60, v51
	global_store_dwordx4 v[56:57], v[48:51], off offset:256
.LBB0_364:
	s_or_b64 exec, exec, s[96:97]
	s_nop 0
	v_add_u32_e32 v50, 0x90, v144
	v_ashrrev_i32_e32 v51, 31, v50
	v_lshlrev_b64 v[48:49], 10, v[50:51]
	v_lshl_add_u64 v[48:49], s[80:81], 0, v[48:49]
	s_and_saveexec_b64 s[0:1], s[8:9]
	s_xor_b64 s[96:97], exec, s[0:1]
	s_cbranch_execz .LBB0_366
	v_pk_add_f32 v[40:41], v[40:41], v[170:171]
	v_pk_add_f32 v[44:45], v[44:45], v[166:167]
	v_pk_add_f32 v[54:55], v[42:43], v[172:173]
	v_mul_f32_e32 v42, 0xbfb8aa3b, v44
	v_mul_f32_e32 v40, 0xbfb8aa3b, v40
	v_exp_f32_e32 v44, v42
	v_mul_f32_e32 v42, 0xbfb8aa3b, v45
	v_exp_f32_e32 v45, v40
	v_pk_add_f32 v[46:47], v[46:47], v[168:169]
	v_mul_f32_e32 v40, 0xbfb8aa3b, v41
	v_exp_f32_e32 v52, v42
	v_mul_f32_e32 v42, 0xbfb8aa3b, v46
	v_exp_f32_e32 v53, v40
	v_mul_f32_e32 v40, 0xbfb8aa3b, v54
	v_exp_f32_e32 v46, v42
	v_mul_f32_e32 v42, 0xbfb8aa3b, v47
	v_exp_f32_e32 v47, v40
	v_mul_f32_e32 v40, 0xbfb8aa3b, v55
	v_exp_f32_e32 v43, v40
	v_pk_add_f32 v[40:41], v[44:45], 1.0 op_sel_hi:[1,0]
	v_pk_add_f32 v[46:47], v[46:47], 1.0 op_sel_hi:[1,0]
	v_exp_f32_e32 v42, v42
	v_rcp_f32_e32 v41, v41
	v_pk_add_f32 v[42:43], v[42:43], 1.0 op_sel_hi:[1,0]
	v_rcp_f32_e32 v40, v40
	v_pk_add_f32 v[44:45], v[52:53], 1.0 op_sel_hi:[1,0]
	v_pk_fma_f32 v[40:41], v[40:41], s[28:29], 0.5 op_sel_hi:[1,0,0]
	v_rcp_f32_e32 v45, v45
	v_rcp_f32_e32 v44, v44
	v_rcp_f32_e32 v47, v47
	v_rcp_f32_e32 v46, v46
	v_rcp_f32_e32 v43, v43
	v_rcp_f32_e32 v42, v42
	v_cvt_u32_f32_e32 v52, v41
	v_cvt_u32_f32_e32 v53, v40
	v_pk_fma_f32 v[40:41], v[44:45], s[28:29], 0.5 op_sel_hi:[1,0,0]
	s_nop 0
	v_cvt_u32_f32_e32 v40, v40
	v_cvt_u32_f32_e32 v41, v41
	v_lshlrev_b32_e32 v40, 8, v40
	v_lshlrev_b32_e32 v41, 8, v41
	v_or_b32_e32 v44, v41, v52
	v_or_b32_e32 v45, v40, v53
	v_pk_fma_f32 v[40:41], v[46:47], s[28:29], 0.5 op_sel_hi:[1,0,0]
	s_nop 0
	v_cvt_u32_f32_sdwa v40, v40 dst_sel:WORD_1 dst_unused:UNUSED_PAD src0_sel:DWORD
	v_cvt_u32_f32_sdwa v41, v41 dst_sel:WORD_1 dst_unused:UNUSED_PAD src0_sel:DWORD
	v_or_b32_e32 v45, v45, v40
	v_or_b32_e32 v44, v44, v41
	v_pk_fma_f32 v[40:41], v[42:43], s[28:29], 0.5 op_sel_hi:[1,0,0]
	v_lshl_add_u64 v[42:43], v[48:49], 0, v[136:137]
	v_cvt_u32_f32_sdwa v40, v40 dst_sel:BYTE_3 dst_unused:UNUSED_PAD src0_sel:DWORD
	v_cvt_u32_f32_sdwa v41, v41 dst_sel:BYTE_3 dst_unused:UNUSED_PAD src0_sel:DWORD
	v_or_b32_e32 v40, v45, v40
	v_or_b32_e32 v41, v44, v41
	global_store_dwordx2 v[42:43], v[40:41], off

.LBB0_369:
	v_pk_add_f32 v[32:33], v[32:33], v[178:179]
	v_pk_add_f32 v[36:37], v[36:37], v[174:175]
	v_pk_add_f32 v[34:35], v[34:35], v[180:181]
	v_mul_f32_e32 v36, 0xbfb8aa3b, v36
	v_exp_f32_e32 v36, v36
	v_mul_f32_e32 v37, 0xbfb8aa3b, v37
	v_exp_f32_e32 v37, v37
	v_pk_add_f32 v[38:39], v[38:39], v[176:177]
	v_add_f32_e32 v36, 1.0, v36
	v_add_f32_e32 v37, 1.0, v37
	v_mul_f32_e32 v38, 0xbfb8aa3b, v38
	v_exp_f32_e32 v38, v38
	v_rcp_f32_e32 v36, v36
	v_add_f32_e32 v38, 1.0, v38
	v_mul_f32_e32 v39, 0xbfb8aa3b, v39
	v_exp_f32_e32 v39, v39
	v_rcp_f32_e32 v37, v37
	v_add_f32_e32 v39, 1.0, v39
	v_mul_f32_e32 v32, 0xbfb8aa3b, v32
	v_exp_f32_e32 v32, v32
	v_rcp_f32_e32 v38, v38
	v_add_f32_e32 v32, 1.0, v32
	v_mul_f32_e32 v36, 0xbf60028a, v36
	v_mul_f32_e32 v37, 0xbf60028a, v37
	v_rcp_f32_e32 v39, v39
	v_mul_f32_e32 v38, 0xbf60028a, v38
	v_mul_f32_e32 v39, 0xbf60028a, v39
	v_rcp_f32_e32 v32, v32
	s_nop 0
	v_mul_f32_e32 v42, 0xbf60028a, v32
	v_mul_f32_e32 v32, 0xbfb8aa3b, v33
	v_exp_f32_e32 v32, v32
	s_nop 0
	v_add_f32_e32 v32, 1.0, v32
	v_rcp_f32_e32 v32, v32
	s_nop 0
	v_mul_f32_e32 v43, 0xbf60028a, v32
	v_mul_f32_e32 v32, 0xbfb8aa3b, v34
	v_exp_f32_e32 v32, v32
	s_nop 0
	v_add_f32_e32 v32, 1.0, v32
	v_rcp_f32_e32 v32, v32
	s_nop 0
	v_mul_f32_e32 v44, 0xbf60028a, v32
	v_mul_f32_e32 v32, 0xbfb8aa3b, v35
	v_exp_f32_e32 v32, v32
	s_nop 0
	v_add_f32_e32 v32, 1.0, v32
	v_rcp_f32_e32 v32, v32
	s_nop 0
	v_mul_f32_e32 v35, 0xbf60028a, v32
	v_lshl_add_u64 v[40:41], v[142:143], 1, v[50:51]
	v_cvt_pk_bf16_f32 v32, v36, v37
	v_cvt_pk_bf16_f32 v33, v38, v39
	v_cvt_pk_bf16_f32 v34, v42, v43
	v_cvt_pk_bf16_f32 v35, v44, v35
	global_store_dwordx4 v[40:41], v[32:35], off offset:256
.LBB0_370:
	s_or_b64 exec, exec, s[96:97]
	s_nop 0
	v_add_u32_e32 v34, 0xa0, v144
	v_ashrrev_i32_e32 v35, 31, v34
	v_lshlrev_b64 v[32:33], 10, v[34:35]
	v_lshl_add_u64 v[32:33], s[80:81], 0, v[32:33]
	s_and_saveexec_b64 s[0:1], s[8:9]
	s_xor_b64 s[96:97], exec, s[0:1]
	s_cbranch_execz .LBB0_372
	v_pk_add_f32 v[24:25], v[24:25], v[170:171]
	v_pk_add_f32 v[28:29], v[28:29], v[166:167]
	v_pk_add_f32 v[38:39], v[26:27], v[172:173]
	v_mul_f32_e32 v26, 0xbfb8aa3b, v28
	v_mul_f32_e32 v24, 0xbfb8aa3b, v24
	v_exp_f32_e32 v28, v26
	v_mul_f32_e32 v26, 0xbfb8aa3b, v29
	v_exp_f32_e32 v29, v24
	v_pk_add_f32 v[30:31], v[30:31], v[168:169]
	v_mul_f32_e32 v24, 0xbfb8aa3b, v25
	v_exp_f32_e32 v36, v26
	v_mul_f32_e32 v26, 0xbfb8aa3b, v30
	v_exp_f32_e32 v37, v24
	v_mul_f32_e32 v24, 0xbfb8aa3b, v38
	v_exp_f32_e32 v30, v26
	v_mul_f32_e32 v26, 0xbfb8aa3b, v31
	v_exp_f32_e32 v31, v24
	v_mul_f32_e32 v24, 0xbfb8aa3b, v39
	v_exp_f32_e32 v27, v24
	v_pk_add_f32 v[24:25], v[28:29], 1.0 op_sel_hi:[1,0]
	v_pk_add_f32 v[30:31], v[30:31], 1.0 op_sel_hi:[1,0]
	v_exp_f32_e32 v26, v26
	v_rcp_f32_e32 v25, v25
	v_pk_add_f32 v[26:27], v[26:27], 1.0 op_sel_hi:[1,0]
	v_rcp_f32_e32 v24, v24
	v_pk_add_f32 v[28:29], v[36:37], 1.0 op_sel_hi:[1,0]
	v_pk_fma_f32 v[24:25], v[24:25], s[28:29], 0.5 op_sel_hi:[1,0,0]
	v_rcp_f32_e32 v29, v29
	v_rcp_f32_e32 v28, v28
	v_rcp_f32_e32 v31, v31
	v_rcp_f32_e32 v30, v30
	v_rcp_f32_e32 v27, v27
	v_rcp_f32_e32 v26, v26
	v_cvt_u32_f32_e32 v36, v25
	v_cvt_u32_f32_e32 v37, v24
	v_pk_fma_f32 v[24:25], v[28:29], s[28:29], 0.5 op_sel_hi:[1,0,0]
	s_nop 0
	v_cvt_u32_f32_e32 v24, v24
	v_cvt_u32_f32_e32 v25, v25
	v_lshlrev_b32_e32 v24, 8, v24
	v_lshlrev_b32_e32 v25, 8, v25
	v_or_b32_e32 v28, v25, v36
	v_or_b32_e32 v29, v24, v37
	v_pk_fma_f32 v[24:25], v[30:31], s[28:29], 0.5 op_sel_hi:[1,0,0]
	s_nop 0
	v_cvt_u32_f32_sdwa v24, v24 dst_sel:WORD_1 dst_unused:UNUSED_PAD src0_sel:DWORD
	v_cvt_u32_f32_sdwa v25, v25 dst_sel:WORD_1 dst_unused:UNUSED_PAD src0_sel:DWORD
	v_or_b32_e32 v29, v29, v24
	v_or_b32_e32 v28, v28, v25
	v_pk_fma_f32 v[24:25], v[26:27], s[28:29], 0.5 op_sel_hi:[1,0,0]
	v_lshl_add_u64 v[26:27], v[32:33], 0, v[136:137]
	v_cvt_u32_f32_sdwa v24, v24 dst_sel:BYTE_3 dst_unused:UNUSED_PAD src0_sel:DWORD
	v_cvt_u32_f32_sdwa v25, v25 dst_sel:BYTE_3 dst_unused:UNUSED_PAD src0_sel:DWORD
	v_or_b32_e32 v24, v29, v24
	v_or_b32_e32 v25, v28, v25
	global_store_dwordx2 v[26:27], v[24:25], off

.LBB0_375:
	v_pk_add_f32 v[16:17], v[16:17], v[178:179]
	v_pk_add_f32 v[20:21], v[20:21], v[174:175]
	v_pk_add_f32 v[18:19], v[18:19], v[180:181]
	v_mul_f32_e32 v20, 0xbfb8aa3b, v20
	v_exp_f32_e32 v20, v20
	v_mul_f32_e32 v21, 0xbfb8aa3b, v21
	v_exp_f32_e32 v21, v21
	v_pk_add_f32 v[22:23], v[22:23], v[176:177]
	v_add_f32_e32 v20, 1.0, v20
	v_add_f32_e32 v21, 1.0, v21
	v_mul_f32_e32 v22, 0xbfb8aa3b, v22
	v_exp_f32_e32 v22, v22
	v_rcp_f32_e32 v20, v20
	v_add_f32_e32 v22, 1.0, v22
	v_mul_f32_e32 v23, 0xbfb8aa3b, v23
	v_exp_f32_e32 v23, v23
	v_rcp_f32_e32 v21, v21
	v_add_f32_e32 v23, 1.0, v23
	v_mul_f32_e32 v16, 0xbfb8aa3b, v16
	v_exp_f32_e32 v16, v16
	v_rcp_f32_e32 v22, v22
	v_add_f32_e32 v16, 1.0, v16
	v_mul_f32_e32 v20, 0xbf60028a, v20
	v_mul_f32_e32 v21, 0xbf60028a, v21
	v_rcp_f32_e32 v23, v23
	v_mul_f32_e32 v22, 0xbf60028a, v22
	v_mul_f32_e32 v23, 0xbf60028a, v23
	v_rcp_f32_e32 v16, v16
	s_nop 0
	v_mul_f32_e32 v26, 0xbf60028a, v16
	v_mul_f32_e32 v16, 0xbfb8aa3b, v17
	v_exp_f32_e32 v16, v16
	s_nop 0
	v_add_f32_e32 v16, 1.0, v16
	v_rcp_f32_e32 v16, v16
	s_nop 0
	v_mul_f32_e32 v27, 0xbf60028a, v16
	v_mul_f32_e32 v16, 0xbfb8aa3b, v18
	v_exp_f32_e32 v16, v16
	s_nop 0
	v_add_f32_e32 v16, 1.0, v16
	v_rcp_f32_e32 v16, v16
	s_nop 0
	v_mul_f32_e32 v28, 0xbf60028a, v16
	v_mul_f32_e32 v16, 0xbfb8aa3b, v19
	v_exp_f32_e32 v16, v16
	s_nop 0
	v_add_f32_e32 v16, 1.0, v16
	v_rcp_f32_e32 v16, v16
	s_nop 0
	v_mul_f32_e32 v19, 0xbf60028a, v16
	v_lshl_add_u64 v[24:25], v[142:143], 1, v[34:35]
	v_cvt_pk_bf16_f32 v16, v20, v21
	v_cvt_pk_bf16_f32 v17, v22, v23
	v_cvt_pk_bf16_f32 v18, v26, v27
	v_cvt_pk_bf16_f32 v19, v28, v19
	global_store_dwordx4 v[24:25], v[16:19], off offset:256
.LBB0_376:
	s_or_b64 exec, exec, s[96:97]
	s_nop 0
	v_add_u32_e32 v18, 0xb0, v144
	v_ashrrev_i32_e32 v19, 31, v18
	v_lshlrev_b64 v[16:17], 10, v[18:19]
	v_lshl_add_u64 v[16:17], s[80:81], 0, v[16:17]
	s_and_saveexec_b64 s[0:1], s[8:9]
	s_xor_b64 s[8:9], exec, s[0:1]
	s_cbranch_execz .LBB0_378
	v_pk_add_f32 v[8:9], v[8:9], v[170:171]
	v_pk_add_f32 v[12:13], v[12:13], v[166:167]
	v_pk_add_f32 v[22:23], v[10:11], v[172:173]
	v_mul_f32_e32 v10, 0xbfb8aa3b, v12
	v_mul_f32_e32 v8, 0xbfb8aa3b, v8
	v_exp_f32_e32 v12, v10
	v_mul_f32_e32 v10, 0xbfb8aa3b, v13
	v_exp_f32_e32 v13, v8
	v_pk_add_f32 v[14:15], v[14:15], v[168:169]
	v_mul_f32_e32 v8, 0xbfb8aa3b, v9
	v_exp_f32_e32 v20, v10
	v_mul_f32_e32 v10, 0xbfb8aa3b, v14
	v_exp_f32_e32 v21, v8
	v_mul_f32_e32 v8, 0xbfb8aa3b, v22
	v_exp_f32_e32 v14, v10
	v_mul_f32_e32 v10, 0xbfb8aa3b, v15
	v_exp_f32_e32 v15, v8
	v_mul_f32_e32 v8, 0xbfb8aa3b, v23
	v_exp_f32_e32 v11, v8
	v_pk_add_f32 v[8:9], v[12:13], 1.0 op_sel_hi:[1,0]
	v_pk_add_f32 v[14:15], v[14:15], 1.0 op_sel_hi:[1,0]
	v_exp_f32_e32 v10, v10
	v_rcp_f32_e32 v9, v9
	v_pk_add_f32 v[10:11], v[10:11], 1.0 op_sel_hi:[1,0]
	v_rcp_f32_e32 v8, v8
	v_pk_add_f32 v[12:13], v[20:21], 1.0 op_sel_hi:[1,0]
	v_pk_fma_f32 v[8:9], v[8:9], s[28:29], 0.5 op_sel_hi:[1,0,0]
	v_rcp_f32_e32 v13, v13
	v_rcp_f32_e32 v12, v12
	v_rcp_f32_e32 v15, v15
	v_rcp_f32_e32 v14, v14
	v_rcp_f32_e32 v11, v11
	v_rcp_f32_e32 v10, v10
	v_cvt_u32_f32_e32 v20, v9
	v_cvt_u32_f32_e32 v21, v8
	v_pk_fma_f32 v[8:9], v[12:13], s[28:29], 0.5 op_sel_hi:[1,0,0]
	s_nop 0
	v_cvt_u32_f32_e32 v8, v8
	v_cvt_u32_f32_e32 v9, v9
	v_lshlrev_b32_e32 v8, 8, v8
	v_lshlrev_b32_e32 v9, 8, v9
	v_or_b32_e32 v12, v9, v20
	v_or_b32_e32 v13, v8, v21
	v_pk_fma_f32 v[8:9], v[14:15], s[28:29], 0.5 op_sel_hi:[1,0,0]
	s_nop 0
	v_cvt_u32_f32_sdwa v8, v8 dst_sel:WORD_1 dst_unused:UNUSED_PAD src0_sel:DWORD
	v_cvt_u32_f32_sdwa v9, v9 dst_sel:WORD_1 dst_unused:UNUSED_PAD src0_sel:DWORD
	v_or_b32_e32 v13, v13, v8
	v_or_b32_e32 v12, v12, v9
	v_pk_fma_f32 v[8:9], v[10:11], s[28:29], 0.5 op_sel_hi:[1,0,0]
	v_lshl_add_u64 v[10:11], v[16:17], 0, v[136:137]
	v_cvt_u32_f32_sdwa v8, v8 dst_sel:BYTE_3 dst_unused:UNUSED_PAD src0_sel:DWORD
	v_cvt_u32_f32_sdwa v9, v9 dst_sel:BYTE_3 dst_unused:UNUSED_PAD src0_sel:DWORD
	v_or_b32_e32 v8, v13, v8
	v_or_b32_e32 v9, v12, v9
	global_store_dwordx2 v[10:11], v[8:9], off

.LBB0_382:
	v_pk_add_f32 v[104:105], v[104:105], v[170:171]
	v_pk_add_f32 v[108:109], v[108:109], v[166:167]
	v_pk_add_f32 v[106:107], v[106:107], v[172:173]
	v_mul_f32_e32 v108, 0xbfb8aa3b, v108
	v_exp_f32_e32 v108, v108
	v_mul_f32_e32 v109, 0xbfb8aa3b, v109
	v_exp_f32_e32 v109, v109
	v_pk_add_f32 v[110:111], v[110:111], v[168:169]
	v_add_f32_e32 v108, 1.0, v108
	v_add_f32_e32 v109, 1.0, v109
	v_mul_f32_e32 v110, 0xbfb8aa3b, v110
	v_exp_f32_e32 v110, v110
	v_rcp_f32_e32 v108, v108
	v_add_f32_e32 v110, 1.0, v110
	v_mul_f32_e32 v111, 0xbfb8aa3b, v111
	v_exp_f32_e32 v111, v111
	v_rcp_f32_e32 v109, v109
	v_add_f32_e32 v111, 1.0, v111
	v_mul_f32_e32 v104, 0xbfb8aa3b, v104
	v_exp_f32_e32 v104, v104
	v_rcp_f32_e32 v110, v110
	v_add_f32_e32 v104, 1.0, v104
	v_mul_f32_e32 v108, 0xbf60028a, v108
	v_mul_f32_e32 v109, 0xbf60028a, v109
	v_rcp_f32_e32 v111, v111
	v_mul_f32_e32 v110, 0xbf60028a, v110
	v_mul_f32_e32 v111, 0xbf60028a, v111
	v_rcp_f32_e32 v104, v104
	s_nop 0
	v_mul_f32_e32 v118, 0xbf60028a, v104
	v_mul_f32_e32 v104, 0xbfb8aa3b, v105
	v_exp_f32_e32 v104, v104
	s_nop 0
	v_add_f32_e32 v104, 1.0, v104
	v_rcp_f32_e32 v104, v104
	s_nop 0
	v_mul_f32_e32 v119, 0xbf60028a, v104
	v_mul_f32_e32 v104, 0xbfb8aa3b, v106
	v_exp_f32_e32 v104, v104
	s_nop 0
	v_add_f32_e32 v104, 1.0, v104
	v_rcp_f32_e32 v104, v104
	s_nop 0
	v_mul_f32_e32 v121, 0xbf60028a, v104
	v_mul_f32_e32 v104, 0xbfb8aa3b, v107
	v_exp_f32_e32 v104, v104
	s_nop 0
	v_add_f32_e32 v104, 1.0, v104
	v_rcp_f32_e32 v104, v104
	s_nop 0
	v_mul_f32_e32 v107, 0xbf60028a, v104
	v_lshl_add_u64 v[116:117], v[142:143], 1, v[114:115]
	v_cvt_pk_bf16_f32 v104, v108, v109
	v_cvt_pk_bf16_f32 v105, v110, v111
	v_cvt_pk_bf16_f32 v106, v118, v119
	v_cvt_pk_bf16_f32 v107, v121, v107
	global_store_dwordx4 v[116:117], v[104:107], off
	s_or_b64 exec, exec, s[96:97]
	s_and_saveexec_b64 s[0:1], s[10:11]
	s_xor_b64 s[96:97], exec, s[0:1]
	s_cbranch_execz .LBB0_344
.LBB0_383:
	v_mov_b32_e32 v121, v137
	v_pk_add_f32 v[96:97], v[96:97], v[178:179]
	v_pk_add_f32 v[100:101], v[100:101], v[174:175]
	v_pk_add_f32 v[106:107], v[98:99], v[180:181]
	v_mul_f32_e32 v98, 0xbfb8aa3b, v100
	v_mul_f32_e32 v96, 0xbfb8aa3b, v96
	v_exp_f32_e32 v100, v98
	v_mul_f32_e32 v98, 0xbfb8aa3b, v101
	v_exp_f32_e32 v101, v96
	v_pk_add_f32 v[102:103], v[102:103], v[176:177]
	v_mul_f32_e32 v96, 0xbfb8aa3b, v97
	v_exp_f32_e32 v104, v98
	v_mul_f32_e32 v98, 0xbfb8aa3b, v102
	v_exp_f32_e32 v105, v96
	v_mul_f32_e32 v96, 0xbfb8aa3b, v106
	v_exp_f32_e32 v102, v98
	v_mul_f32_e32 v98, 0xbfb8aa3b, v103
	v_exp_f32_e32 v103, v96
	v_mul_f32_e32 v96, 0xbfb8aa3b, v107
	v_exp_f32_e32 v99, v96
	v_pk_add_f32 v[96:97], v[100:101], 1.0 op_sel_hi:[1,0]
	v_pk_add_f32 v[102:103], v[102:103], 1.0 op_sel_hi:[1,0]
	v_exp_f32_e32 v98, v98
	v_rcp_f32_e32 v97, v97
	v_pk_add_f32 v[98:99], v[98:99], 1.0 op_sel_hi:[1,0]
	v_rcp_f32_e32 v96, v96
	v_pk_add_f32 v[100:101], v[104:105], 1.0 op_sel_hi:[1,0]
	v_pk_fma_f32 v[96:97], v[96:97], s[28:29], 0.5 op_sel_hi:[1,0,0]
	v_rcp_f32_e32 v101, v101
	v_rcp_f32_e32 v100, v100
	v_rcp_f32_e32 v103, v103
	v_rcp_f32_e32 v102, v102
	v_rcp_f32_e32 v99, v99
	v_rcp_f32_e32 v98, v98
	v_cvt_u32_f32_e32 v104, v97
	v_cvt_u32_f32_e32 v105, v96
	v_pk_fma_f32 v[96:97], v[100:101], s[28:29], 0.5 op_sel_hi:[1,0,0]
	s_nop 0
	v_cvt_u32_f32_e32 v96, v96
	v_cvt_u32_f32_e32 v97, v97
	v_lshlrev_b32_e32 v96, 8, v96
	v_lshlrev_b32_e32 v97, 8, v97
	v_or_b32_e32 v100, v97, v104
	v_or_b32_e32 v101, v96, v105
	v_pk_fma_f32 v[96:97], v[102:103], s[28:29], 0.5 op_sel_hi:[1,0,0]
	s_nop 0
	v_cvt_u32_f32_sdwa v96, v96 dst_sel:WORD_1 dst_unused:UNUSED_PAD src0_sel:DWORD
	v_cvt_u32_f32_sdwa v97, v97 dst_sel:WORD_1 dst_unused:UNUSED_PAD src0_sel:DWORD
	v_or_b32_e32 v101, v101, v96
	v_or_b32_e32 v100, v100, v97
	v_pk_fma_f32 v[96:97], v[98:99], s[28:29], 0.5 op_sel_hi:[1,0,0]
	v_lshl_add_u64 v[98:99], v[112:113], 0, v[120:121]
	v_cvt_u32_f32_sdwa v96, v96 dst_sel:BYTE_3 dst_unused:UNUSED_PAD src0_sel:DWORD
	v_cvt_u32_f32_sdwa v97, v97 dst_sel:BYTE_3 dst_unused:UNUSED_PAD src0_sel:DWORD
	v_or_b32_e32 v96, v101, v96
	v_or_b32_e32 v97, v100, v97
	global_store_dwordx2 v[98:99], v[96:97], off
	s_andn2_saveexec_b64 s[96:97], s[96:97]
	s_cbranch_execnz .LBB0_345
	s_branch .LBB0_346
.LBB0_384:
	v_pk_add_f32 v[88:89], v[88:89], v[170:171]
	v_pk_add_f32 v[92:93], v[92:93], v[166:167]
	v_pk_add_f32 v[90:91], v[90:91], v[172:173]
	v_mul_f32_e32 v92, 0xbfb8aa3b, v92
	v_exp_f32_e32 v92, v92
	v_mul_f32_e32 v93, 0xbfb8aa3b, v93
	v_exp_f32_e32 v93, v93
	v_pk_add_f32 v[94:95], v[94:95], v[168:169]
	v_add_f32_e32 v92, 1.0, v92
	v_add_f32_e32 v93, 1.0, v93
	v_mul_f32_e32 v94, 0xbfb8aa3b, v94
	v_exp_f32_e32 v94, v94
	v_rcp_f32_e32 v92, v92
	v_add_f32_e32 v94, 1.0, v94
	v_mul_f32_e32 v95, 0xbfb8aa3b, v95
	v_exp_f32_e32 v95, v95
	v_rcp_f32_e32 v93, v93
	v_add_f32_e32 v95, 1.0, v95
	v_mul_f32_e32 v88, 0xbfb8aa3b, v88
	v_exp_f32_e32 v88, v88
	v_rcp_f32_e32 v94, v94
	v_add_f32_e32 v88, 1.0, v88
	v_mul_f32_e32 v92, 0xbf60028a, v92
	v_mul_f32_e32 v93, 0xbf60028a, v93
	v_rcp_f32_e32 v95, v95
	v_mul_f32_e32 v94, 0xbf60028a, v94
	v_mul_f32_e32 v95, 0xbf60028a, v95
	v_rcp_f32_e32 v88, v88
	s_nop 0
	v_mul_f32_e32 v102, 0xbf60028a, v88
	v_mul_f32_e32 v88, 0xbfb8aa3b, v89
	v_exp_f32_e32 v88, v88
	s_nop 0
	v_add_f32_e32 v88, 1.0, v88
	v_rcp_f32_e32 v88, v88
	s_nop 0
	v_mul_f32_e32 v103, 0xbf60028a, v88
	v_mul_f32_e32 v88, 0xbfb8aa3b, v90
	v_exp_f32_e32 v88, v88
	s_nop 0
	v_add_f32_e32 v88, 1.0, v88
	v_rcp_f32_e32 v88, v88
	s_nop 0
	v_mul_f32_e32 v104, 0xbf60028a, v88
	v_mul_f32_e32 v88, 0xbfb8aa3b, v91
	v_exp_f32_e32 v88, v88
	s_nop 0
	v_add_f32_e32 v88, 1.0, v88
	v_rcp_f32_e32 v88, v88
	s_nop 0
	v_mul_f32_e32 v91, 0xbf60028a, v88
	v_lshl_add_u64 v[100:101], v[142:143], 1, v[98:99]
	v_cvt_pk_bf16_f32 v88, v92, v93
	v_cvt_pk_bf16_f32 v89, v94, v95
	v_cvt_pk_bf16_f32 v90, v102, v103
	v_cvt_pk_bf16_f32 v91, v104, v91
	global_store_dwordx4 v[100:101], v[88:91], off
	s_or_b64 exec, exec, s[96:97]
	s_and_saveexec_b64 s[0:1], s[10:11]
	s_xor_b64 s[96:97], exec, s[0:1]
	s_cbranch_execz .LBB0_350
.LBB0_385:
	v_mov_b32_e32 v121, v137
	v_pk_add_f32 v[80:81], v[80:81], v[178:179]
	v_pk_add_f32 v[84:85], v[84:85], v[174:175]
	v_pk_add_f32 v[90:91], v[82:83], v[180:181]
	v_mul_f32_e32 v82, 0xbfb8aa3b, v84
	v_mul_f32_e32 v80, 0xbfb8aa3b, v80
	v_exp_f32_e32 v84, v82
	v_mul_f32_e32 v82, 0xbfb8aa3b, v85
	v_exp_f32_e32 v85, v80
	v_pk_add_f32 v[86:87], v[86:87], v[176:177]
	v_mul_f32_e32 v80, 0xbfb8aa3b, v81
	v_exp_f32_e32 v88, v82
	v_mul_f32_e32 v82, 0xbfb8aa3b, v86
	v_exp_f32_e32 v89, v80
	v_mul_f32_e32 v80, 0xbfb8aa3b, v90
	v_exp_f32_e32 v86, v82
	v_mul_f32_e32 v82, 0xbfb8aa3b, v87
	v_exp_f32_e32 v87, v80
	v_mul_f32_e32 v80, 0xbfb8aa3b, v91
	v_exp_f32_e32 v83, v80
	v_pk_add_f32 v[80:81], v[84:85], 1.0 op_sel_hi:[1,0]
	v_pk_add_f32 v[86:87], v[86:87], 1.0 op_sel_hi:[1,0]
	v_exp_f32_e32 v82, v82
	v_rcp_f32_e32 v81, v81
	v_pk_add_f32 v[82:83], v[82:83], 1.0 op_sel_hi:[1,0]
	v_rcp_f32_e32 v80, v80
	v_pk_add_f32 v[84:85], v[88:89], 1.0 op_sel_hi:[1,0]
	v_pk_fma_f32 v[80:81], v[80:81], s[28:29], 0.5 op_sel_hi:[1,0,0]
	v_rcp_f32_e32 v85, v85
	v_rcp_f32_e32 v84, v84
	v_rcp_f32_e32 v87, v87
	v_rcp_f32_e32 v86, v86
	v_rcp_f32_e32 v83, v83
	v_rcp_f32_e32 v82, v82
	v_cvt_u32_f32_e32 v88, v81
	v_cvt_u32_f32_e32 v89, v80
	v_pk_fma_f32 v[80:81], v[84:85], s[28:29], 0.5 op_sel_hi:[1,0,0]
	s_nop 0
	v_cvt_u32_f32_e32 v80, v80
	v_cvt_u32_f32_e32 v81, v81
	v_lshlrev_b32_e32 v80, 8, v80
	v_lshlrev_b32_e32 v81, 8, v81
	v_or_b32_e32 v84, v81, v88
	v_or_b32_e32 v85, v80, v89
	v_pk_fma_f32 v[80:81], v[86:87], s[28:29], 0.5 op_sel_hi:[1,0,0]
	s_nop 0
	v_cvt_u32_f32_sdwa v80, v80 dst_sel:WORD_1 dst_unused:UNUSED_PAD src0_sel:DWORD
	v_cvt_u32_f32_sdwa v81, v81 dst_sel:WORD_1 dst_unused:UNUSED_PAD src0_sel:DWORD
	v_or_b32_e32 v85, v85, v80
	v_or_b32_e32 v84, v84, v81
	v_pk_fma_f32 v[80:81], v[82:83], s[28:29], 0.5 op_sel_hi:[1,0,0]
	v_lshl_add_u64 v[82:83], v[96:97], 0, v[120:121]
	v_cvt_u32_f32_sdwa v80, v80 dst_sel:BYTE_3 dst_unused:UNUSED_PAD src0_sel:DWORD
	v_cvt_u32_f32_sdwa v81, v81 dst_sel:BYTE_3 dst_unused:UNUSED_PAD src0_sel:DWORD
	v_or_b32_e32 v80, v85, v80
	v_or_b32_e32 v81, v84, v81
	global_store_dwordx2 v[82:83], v[80:81], off
	s_andn2_saveexec_b64 s[96:97], s[96:97]
	s_cbranch_execnz .LBB0_351
	s_branch .LBB0_352
.LBB0_386:
	v_pk_add_f32 v[72:73], v[72:73], v[170:171]
	v_pk_add_f32 v[76:77], v[76:77], v[166:167]
	v_pk_add_f32 v[74:75], v[74:75], v[172:173]
	v_mul_f32_e32 v76, 0xbfb8aa3b, v76
	v_exp_f32_e32 v76, v76
	v_mul_f32_e32 v77, 0xbfb8aa3b, v77
	v_exp_f32_e32 v77, v77
	v_pk_add_f32 v[78:79], v[78:79], v[168:169]
	v_add_f32_e32 v76, 1.0, v76
	v_add_f32_e32 v77, 1.0, v77
	v_mul_f32_e32 v78, 0xbfb8aa3b, v78
	v_exp_f32_e32 v78, v78
	v_rcp_f32_e32 v76, v76
	v_add_f32_e32 v78, 1.0, v78
	v_mul_f32_e32 v79, 0xbfb8aa3b, v79
	v_exp_f32_e32 v79, v79
	v_rcp_f32_e32 v77, v77
	v_add_f32_e32 v79, 1.0, v79
	v_mul_f32_e32 v72, 0xbfb8aa3b, v72
	v_exp_f32_e32 v72, v72
	v_rcp_f32_e32 v78, v78
	v_add_f32_e32 v72, 1.0, v72
	v_mul_f32_e32 v76, 0xbf60028a, v76
	v_mul_f32_e32 v77, 0xbf60028a, v77
	v_rcp_f32_e32 v79, v79
	v_mul_f32_e32 v78, 0xbf60028a, v78
	v_mul_f32_e32 v79, 0xbf60028a, v79
	v_rcp_f32_e32 v72, v72
	s_nop 0
	v_mul_f32_e32 v86, 0xbf60028a, v72
	v_mul_f32_e32 v72, 0xbfb8aa3b, v73
	v_exp_f32_e32 v72, v72
	s_nop 0
	v_add_f32_e32 v72, 1.0, v72
	v_rcp_f32_e32 v72, v72
	s_nop 0
	v_mul_f32_e32 v87, 0xbf60028a, v72
	v_mul_f32_e32 v72, 0xbfb8aa3b, v74
	v_exp_f32_e32 v72, v72
	s_nop 0
	v_add_f32_e32 v72, 1.0, v72
	v_rcp_f32_e32 v72, v72
	s_nop 0
	v_mul_f32_e32 v88, 0xbf60028a, v72
	v_mul_f32_e32 v72, 0xbfb8aa3b, v75
	v_exp_f32_e32 v72, v72
	s_nop 0
	v_add_f32_e32 v72, 1.0, v72
	v_rcp_f32_e32 v72, v72
	s_nop 0
	v_mul_f32_e32 v75, 0xbf60028a, v72
	v_lshl_add_u64 v[84:85], v[142:143], 1, v[82:83]
	v_cvt_pk_bf16_f32 v72, v76, v77
	v_cvt_pk_bf16_f32 v73, v78, v79
	v_cvt_pk_bf16_f32 v74, v86, v87
	v_cvt_pk_bf16_f32 v75, v88, v75
	global_store_dwordx4 v[84:85], v[72:75], off
	s_or_b64 exec, exec, s[96:97]
	s_and_saveexec_b64 s[0:1], s[10:11]
	s_xor_b64 s[96:97], exec, s[0:1]
	s_cbranch_execz .LBB0_356
.LBB0_387:
	v_mov_b32_e32 v121, v137
	v_pk_add_f32 v[64:65], v[64:65], v[178:179]
	v_pk_add_f32 v[68:69], v[68:69], v[174:175]
	v_pk_add_f32 v[74:75], v[66:67], v[180:181]
	v_mul_f32_e32 v66, 0xbfb8aa3b, v68
	v_mul_f32_e32 v64, 0xbfb8aa3b, v64
	v_exp_f32_e32 v68, v66
	v_mul_f32_e32 v66, 0xbfb8aa3b, v69
	v_exp_f32_e32 v69, v64
	v_pk_add_f32 v[70:71], v[70:71], v[176:177]
	v_mul_f32_e32 v64, 0xbfb8aa3b, v65
	v_exp_f32_e32 v72, v66
	v_mul_f32_e32 v66, 0xbfb8aa3b, v70
	v_exp_f32_e32 v73, v64
	v_mul_f32_e32 v64, 0xbfb8aa3b, v74
	v_exp_f32_e32 v70, v66
	v_mul_f32_e32 v66, 0xbfb8aa3b, v71
	v_exp_f32_e32 v71, v64
	v_mul_f32_e32 v64, 0xbfb8aa3b, v75
	v_exp_f32_e32 v67, v64
	v_pk_add_f32 v[64:65], v[68:69], 1.0 op_sel_hi:[1,0]
	v_pk_add_f32 v[70:71], v[70:71], 1.0 op_sel_hi:[1,0]
	v_exp_f32_e32 v66, v66
	v_rcp_f32_e32 v65, v65
	v_pk_add_f32 v[66:67], v[66:67], 1.0 op_sel_hi:[1,0]
	v_rcp_f32_e32 v64, v64
	v_pk_add_f32 v[68:69], v[72:73], 1.0 op_sel_hi:[1,0]
	v_pk_fma_f32 v[64:65], v[64:65], s[28:29], 0.5 op_sel_hi:[1,0,0]
	v_rcp_f32_e32 v69, v69
	v_rcp_f32_e32 v68, v68
	v_rcp_f32_e32 v71, v71
	v_rcp_f32_e32 v70, v70
	v_rcp_f32_e32 v67, v67
	v_rcp_f32_e32 v66, v66
	v_cvt_u32_f32_e32 v72, v65
	v_cvt_u32_f32_e32 v73, v64
	v_pk_fma_f32 v[64:65], v[68:69], s[28:29], 0.5 op_sel_hi:[1,0,0]
	s_nop 0
	v_cvt_u32_f32_e32 v64, v64
	v_cvt_u32_f32_e32 v65, v65
	v_lshlrev_b32_e32 v64, 8, v64
	v_lshlrev_b32_e32 v65, 8, v65
	v_or_b32_e32 v68, v65, v72
	v_or_b32_e32 v69, v64, v73
	v_pk_fma_f32 v[64:65], v[70:71], s[28:29], 0.5 op_sel_hi:[1,0,0]
	s_nop 0
	v_cvt_u32_f32_sdwa v64, v64 dst_sel:WORD_1 dst_unused:UNUSED_PAD src0_sel:DWORD
	v_cvt_u32_f32_sdwa v65, v65 dst_sel:WORD_1 dst_unused:UNUSED_PAD src0_sel:DWORD
	v_or_b32_e32 v69, v69, v64
	v_or_b32_e32 v68, v68, v65
	v_pk_fma_f32 v[64:65], v[66:67], s[28:29], 0.5 op_sel_hi:[1,0,0]
	v_lshl_add_u64 v[66:67], v[80:81], 0, v[120:121]
	v_cvt_u32_f32_sdwa v64, v64 dst_sel:BYTE_3 dst_unused:UNUSED_PAD src0_sel:DWORD
	v_cvt_u32_f32_sdwa v65, v65 dst_sel:BYTE_3 dst_unused:UNUSED_PAD src0_sel:DWORD
	v_or_b32_e32 v64, v69, v64
	v_or_b32_e32 v65, v68, v65
	global_store_dwordx2 v[66:67], v[64:65], off
	s_andn2_saveexec_b64 s[96:97], s[96:97]
	s_cbranch_execnz .LBB0_357
	s_branch .LBB0_358
.LBB0_388:
	v_pk_add_f32 v[56:57], v[56:57], v[170:171]
	v_pk_add_f32 v[60:61], v[60:61], v[166:167]
	v_pk_add_f32 v[58:59], v[58:59], v[172:173]
	v_mul_f32_e32 v60, 0xbfb8aa3b, v60
	v_exp_f32_e32 v60, v60
	v_mul_f32_e32 v61, 0xbfb8aa3b, v61
	v_exp_f32_e32 v61, v61
	v_pk_add_f32 v[62:63], v[62:63], v[168:169]
	v_add_f32_e32 v60, 1.0, v60
	v_add_f32_e32 v61, 1.0, v61
	v_mul_f32_e32 v62, 0xbfb8aa3b, v62
	v_exp_f32_e32 v62, v62
	v_rcp_f32_e32 v60, v60
	v_add_f32_e32 v62, 1.0, v62
	v_mul_f32_e32 v63, 0xbfb8aa3b, v63
	v_exp_f32_e32 v63, v63
	v_rcp_f32_e32 v61, v61
	v_add_f32_e32 v63, 1.0, v63
	v_mul_f32_e32 v56, 0xbfb8aa3b, v56
	v_exp_f32_e32 v56, v56
	v_rcp_f32_e32 v62, v62
	v_add_f32_e32 v56, 1.0, v56
	v_mul_f32_e32 v60, 0xbf60028a, v60
	v_mul_f32_e32 v61, 0xbf60028a, v61
	v_rcp_f32_e32 v63, v63
	v_mul_f32_e32 v62, 0xbf60028a, v62
	v_mul_f32_e32 v63, 0xbf60028a, v63
	v_rcp_f32_e32 v56, v56
	s_nop 0
	v_mul_f32_e32 v70, 0xbf60028a, v56
	v_mul_f32_e32 v56, 0xbfb8aa3b, v57
	v_exp_f32_e32 v56, v56
	s_nop 0
	v_add_f32_e32 v56, 1.0, v56
	v_rcp_f32_e32 v56, v56
	s_nop 0
	v_mul_f32_e32 v71, 0xbf60028a, v56
	v_mul_f32_e32 v56, 0xbfb8aa3b, v58
	v_exp_f32_e32 v56, v56
	s_nop 0
	v_add_f32_e32 v56, 1.0, v56
	v_rcp_f32_e32 v56, v56
	s_nop 0
	v_mul_f32_e32 v72, 0xbf60028a, v56
	v_mul_f32_e32 v56, 0xbfb8aa3b, v59
	v_exp_f32_e32 v56, v56
	s_nop 0
	v_add_f32_e32 v56, 1.0, v56
	v_rcp_f32_e32 v56, v56
	s_nop 0
	v_mul_f32_e32 v59, 0xbf60028a, v56
	v_lshl_add_u64 v[68:69], v[142:143], 1, v[66:67]
	v_cvt_pk_bf16_f32 v56, v60, v61
	v_cvt_pk_bf16_f32 v57, v62, v63
	v_cvt_pk_bf16_f32 v58, v70, v71
	v_cvt_pk_bf16_f32 v59, v72, v59
	global_store_dwordx4 v[68:69], v[56:59], off
	s_or_b64 exec, exec, s[96:97]
	s_and_saveexec_b64 s[0:1], s[10:11]
	s_xor_b64 s[96:97], exec, s[0:1]
	s_cbranch_execz .LBB0_362
.LBB0_389:
	v_mov_b32_e32 v121, v137
	v_pk_add_f32 v[48:49], v[48:49], v[178:179]
	v_pk_add_f32 v[52:53], v[52:53], v[174:175]
	v_pk_add_f32 v[58:59], v[50:51], v[180:181]
	v_mul_f32_e32 v50, 0xbfb8aa3b, v52
	v_mul_f32_e32 v48, 0xbfb8aa3b, v48
	v_exp_f32_e32 v52, v50
	v_mul_f32_e32 v50, 0xbfb8aa3b, v53
	v_exp_f32_e32 v53, v48
	v_pk_add_f32 v[54:55], v[54:55], v[176:177]
	v_mul_f32_e32 v48, 0xbfb8aa3b, v49
	v_exp_f32_e32 v56, v50
	v_mul_f32_e32 v50, 0xbfb8aa3b, v54
	v_exp_f32_e32 v57, v48
	v_mul_f32_e32 v48, 0xbfb8aa3b, v58
	v_exp_f32_e32 v54, v50
	v_mul_f32_e32 v50, 0xbfb8aa3b, v55
	v_exp_f32_e32 v55, v48
	v_mul_f32_e32 v48, 0xbfb8aa3b, v59
	v_exp_f32_e32 v51, v48
	v_pk_add_f32 v[48:49], v[52:53], 1.0 op_sel_hi:[1,0]
	v_pk_add_f32 v[54:55], v[54:55], 1.0 op_sel_hi:[1,0]
	v_exp_f32_e32 v50, v50
	v_rcp_f32_e32 v49, v49
	v_pk_add_f32 v[50:51], v[50:51], 1.0 op_sel_hi:[1,0]
	v_rcp_f32_e32 v48, v48
	v_pk_add_f32 v[52:53], v[56:57], 1.0 op_sel_hi:[1,0]
	v_pk_fma_f32 v[48:49], v[48:49], s[28:29], 0.5 op_sel_hi:[1,0,0]
	v_rcp_f32_e32 v53, v53
	v_rcp_f32_e32 v52, v52
	v_rcp_f32_e32 v55, v55
	v_rcp_f32_e32 v54, v54
	v_rcp_f32_e32 v51, v51
	v_rcp_f32_e32 v50, v50
	v_cvt_u32_f32_e32 v56, v49
	v_cvt_u32_f32_e32 v57, v48
	v_pk_fma_f32 v[48:49], v[52:53], s[28:29], 0.5 op_sel_hi:[1,0,0]
	s_nop 0
	v_cvt_u32_f32_e32 v48, v48
	v_cvt_u32_f32_e32 v49, v49
	v_lshlrev_b32_e32 v48, 8, v48
	v_lshlrev_b32_e32 v49, 8, v49
	v_or_b32_e32 v52, v49, v56
	v_or_b32_e32 v53, v48, v57
	v_pk_fma_f32 v[48:49], v[54:55], s[28:29], 0.5 op_sel_hi:[1,0,0]
	s_nop 0
	v_cvt_u32_f32_sdwa v48, v48 dst_sel:WORD_1 dst_unused:UNUSED_PAD src0_sel:DWORD
	v_cvt_u32_f32_sdwa v49, v49 dst_sel:WORD_1 dst_unused:UNUSED_PAD src0_sel:DWORD
	v_or_b32_e32 v53, v53, v48
	v_or_b32_e32 v52, v52, v49
	v_pk_fma_f32 v[48:49], v[50:51], s[28:29], 0.5 op_sel_hi:[1,0,0]
	v_lshl_add_u64 v[50:51], v[64:65], 0, v[120:121]
	v_cvt_u32_f32_sdwa v48, v48 dst_sel:BYTE_3 dst_unused:UNUSED_PAD src0_sel:DWORD
	v_cvt_u32_f32_sdwa v49, v49 dst_sel:BYTE_3 dst_unused:UNUSED_PAD src0_sel:DWORD
	v_or_b32_e32 v48, v53, v48
	v_or_b32_e32 v49, v52, v49
	global_store_dwordx2 v[50:51], v[48:49], off
	s_andn2_saveexec_b64 s[96:97], s[96:97]
	s_cbranch_execnz .LBB0_363
	s_branch .LBB0_364
.LBB0_390:
	v_pk_add_f32 v[40:41], v[40:41], v[170:171]
	v_pk_add_f32 v[44:45], v[44:45], v[166:167]
	v_pk_add_f32 v[42:43], v[42:43], v[172:173]
	v_mul_f32_e32 v44, 0xbfb8aa3b, v44
	v_exp_f32_e32 v44, v44
	v_mul_f32_e32 v45, 0xbfb8aa3b, v45
	v_exp_f32_e32 v45, v45
	v_pk_add_f32 v[46:47], v[46:47], v[168:169]
	v_add_f32_e32 v44, 1.0, v44
	v_add_f32_e32 v45, 1.0, v45
	v_mul_f32_e32 v46, 0xbfb8aa3b, v46
	v_exp_f32_e32 v46, v46
	v_rcp_f32_e32 v44, v44
	v_add_f32_e32 v46, 1.0, v46
	v_mul_f32_e32 v47, 0xbfb8aa3b, v47
	v_exp_f32_e32 v47, v47
	v_rcp_f32_e32 v45, v45
	v_add_f32_e32 v47, 1.0, v47
	v_mul_f32_e32 v40, 0xbfb8aa3b, v40
	v_exp_f32_e32 v40, v40
	v_rcp_f32_e32 v46, v46
	v_add_f32_e32 v40, 1.0, v40
	v_mul_f32_e32 v44, 0xbf60028a, v44
	v_mul_f32_e32 v45, 0xbf60028a, v45
	v_rcp_f32_e32 v47, v47
	v_mul_f32_e32 v46, 0xbf60028a, v46
	v_mul_f32_e32 v47, 0xbf60028a, v47
	v_rcp_f32_e32 v40, v40
	s_nop 0
	v_mul_f32_e32 v54, 0xbf60028a, v40
	v_mul_f32_e32 v40, 0xbfb8aa3b, v41
	v_exp_f32_e32 v40, v40
	s_nop 0
	v_add_f32_e32 v40, 1.0, v40
	v_rcp_f32_e32 v40, v40
	s_nop 0
	v_mul_f32_e32 v55, 0xbf60028a, v40
	v_mul_f32_e32 v40, 0xbfb8aa3b, v42
	v_exp_f32_e32 v40, v40
	s_nop 0
	v_add_f32_e32 v40, 1.0, v40
	v_rcp_f32_e32 v40, v40
	s_nop 0
	v_mul_f32_e32 v56, 0xbf60028a, v40
	v_mul_f32_e32 v40, 0xbfb8aa3b, v43
	v_exp_f32_e32 v40, v40
	s_nop 0
	v_add_f32_e32 v40, 1.0, v40
	v_rcp_f32_e32 v40, v40
	s_nop 0
	v_mul_f32_e32 v43, 0xbf60028a, v40
	v_lshl_add_u64 v[52:53], v[142:143], 1, v[50:51]
	v_cvt_pk_bf16_f32 v40, v44, v45
	v_cvt_pk_bf16_f32 v41, v46, v47
	v_cvt_pk_bf16_f32 v42, v54, v55
	v_cvt_pk_bf16_f32 v43, v56, v43
	global_store_dwordx4 v[52:53], v[40:43], off
	s_or_b64 exec, exec, s[96:97]
	s_and_saveexec_b64 s[0:1], s[10:11]
	s_xor_b64 s[96:97], exec, s[0:1]
	s_cbranch_execz .LBB0_368
.LBB0_391:
	v_mov_b32_e32 v121, v137
	v_pk_add_f32 v[32:33], v[32:33], v[178:179]
	v_pk_add_f32 v[36:37], v[36:37], v[174:175]
	v_pk_add_f32 v[42:43], v[34:35], v[180:181]
	v_mul_f32_e32 v34, 0xbfb8aa3b, v36
	v_mul_f32_e32 v32, 0xbfb8aa3b, v32
	v_exp_f32_e32 v36, v34
	v_mul_f32_e32 v34, 0xbfb8aa3b, v37
	v_exp_f32_e32 v37, v32
	v_pk_add_f32 v[38:39], v[38:39], v[176:177]
	v_mul_f32_e32 v32, 0xbfb8aa3b, v33
	v_exp_f32_e32 v40, v34
	v_mul_f32_e32 v34, 0xbfb8aa3b, v38
	v_exp_f32_e32 v41, v32
	v_mul_f32_e32 v32, 0xbfb8aa3b, v42
	v_exp_f32_e32 v38, v34
	v_mul_f32_e32 v34, 0xbfb8aa3b, v39
	v_exp_f32_e32 v39, v32
	v_mul_f32_e32 v32, 0xbfb8aa3b, v43
	v_exp_f32_e32 v35, v32
	v_pk_add_f32 v[32:33], v[36:37], 1.0 op_sel_hi:[1,0]
	v_pk_add_f32 v[38:39], v[38:39], 1.0 op_sel_hi:[1,0]
	v_exp_f32_e32 v34, v34
	v_rcp_f32_e32 v33, v33
	v_pk_add_f32 v[34:35], v[34:35], 1.0 op_sel_hi:[1,0]
	v_rcp_f32_e32 v32, v32
	v_pk_add_f32 v[36:37], v[40:41], 1.0 op_sel_hi:[1,0]
	v_pk_fma_f32 v[32:33], v[32:33], s[28:29], 0.5 op_sel_hi:[1,0,0]
	v_rcp_f32_e32 v37, v37
	v_rcp_f32_e32 v36, v36
	v_rcp_f32_e32 v39, v39
	v_rcp_f32_e32 v38, v38
	v_rcp_f32_e32 v35, v35
	v_rcp_f32_e32 v34, v34
	v_cvt_u32_f32_e32 v40, v33
	v_cvt_u32_f32_e32 v41, v32
	v_pk_fma_f32 v[32:33], v[36:37], s[28:29], 0.5 op_sel_hi:[1,0,0]
	s_nop 0
	v_cvt_u32_f32_e32 v32, v32
	v_cvt_u32_f32_e32 v33, v33
	v_lshlrev_b32_e32 v32, 8, v32
	v_lshlrev_b32_e32 v33, 8, v33
	v_or_b32_e32 v36, v33, v40
	v_or_b32_e32 v37, v32, v41
	v_pk_fma_f32 v[32:33], v[38:39], s[28:29], 0.5 op_sel_hi:[1,0,0]
	s_nop 0
	v_cvt_u32_f32_sdwa v32, v32 dst_sel:WORD_1 dst_unused:UNUSED_PAD src0_sel:DWORD
	v_cvt_u32_f32_sdwa v33, v33 dst_sel:WORD_1 dst_unused:UNUSED_PAD src0_sel:DWORD
	v_or_b32_e32 v37, v37, v32
	v_or_b32_e32 v36, v36, v33
	v_pk_fma_f32 v[32:33], v[34:35], s[28:29], 0.5 op_sel_hi:[1,0,0]
	v_lshl_add_u64 v[34:35], v[48:49], 0, v[120:121]
	v_cvt_u32_f32_sdwa v32, v32 dst_sel:BYTE_3 dst_unused:UNUSED_PAD src0_sel:DWORD
	v_cvt_u32_f32_sdwa v33, v33 dst_sel:BYTE_3 dst_unused:UNUSED_PAD src0_sel:DWORD
	v_or_b32_e32 v32, v37, v32
	v_or_b32_e32 v33, v36, v33
	global_store_dwordx2 v[34:35], v[32:33], off
	s_andn2_saveexec_b64 s[96:97], s[96:97]
	s_cbranch_execnz .LBB0_369
	s_branch .LBB0_370
.LBB0_392:
	v_pk_add_f32 v[24:25], v[24:25], v[170:171]
	v_pk_add_f32 v[28:29], v[28:29], v[166:167]
	v_pk_add_f32 v[26:27], v[26:27], v[172:173]
	v_mul_f32_e32 v28, 0xbfb8aa3b, v28
	v_exp_f32_e32 v28, v28
	v_mul_f32_e32 v29, 0xbfb8aa3b, v29
	v_exp_f32_e32 v29, v29
	v_pk_add_f32 v[30:31], v[30:31], v[168:169]
	v_add_f32_e32 v28, 1.0, v28
	v_add_f32_e32 v29, 1.0, v29
	v_mul_f32_e32 v30, 0xbfb8aa3b, v30
	v_exp_f32_e32 v30, v30
	v_rcp_f32_e32 v28, v28
	v_add_f32_e32 v30, 1.0, v30
	v_mul_f32_e32 v31, 0xbfb8aa3b, v31
	v_exp_f32_e32 v31, v31
	v_rcp_f32_e32 v29, v29
	v_add_f32_e32 v31, 1.0, v31
	v_mul_f32_e32 v24, 0xbfb8aa3b, v24
	v_exp_f32_e32 v24, v24
	v_rcp_f32_e32 v30, v30
	v_add_f32_e32 v24, 1.0, v24
	v_mul_f32_e32 v28, 0xbf60028a, v28
	v_mul_f32_e32 v29, 0xbf60028a, v29
	v_rcp_f32_e32 v31, v31
	v_mul_f32_e32 v30, 0xbf60028a, v30
	v_mul_f32_e32 v31, 0xbf60028a, v31
	v_rcp_f32_e32 v24, v24
	s_nop 0
	v_mul_f32_e32 v38, 0xbf60028a, v24
	v_mul_f32_e32 v24, 0xbfb8aa3b, v25
	v_exp_f32_e32 v24, v24
	s_nop 0
	v_add_f32_e32 v24, 1.0, v24
	v_rcp_f32_e32 v24, v24
	s_nop 0
	v_mul_f32_e32 v39, 0xbf60028a, v24
	v_mul_f32_e32 v24, 0xbfb8aa3b, v26
	v_exp_f32_e32 v24, v24
	s_nop 0
	v_add_f32_e32 v24, 1.0, v24
	v_rcp_f32_e32 v24, v24
	s_nop 0
	v_mul_f32_e32 v40, 0xbf60028a, v24
	v_mul_f32_e32 v24, 0xbfb8aa3b, v27
	v_exp_f32_e32 v24, v24
	s_nop 0
	v_add_f32_e32 v24, 1.0, v24
	v_rcp_f32_e32 v24, v24
	s_nop 0
	v_mul_f32_e32 v27, 0xbf60028a, v24
	v_lshl_add_u64 v[36:37], v[142:143], 1, v[34:35]
	v_cvt_pk_bf16_f32 v24, v28, v29
	v_cvt_pk_bf16_f32 v25, v30, v31
	v_cvt_pk_bf16_f32 v26, v38, v39
	v_cvt_pk_bf16_f32 v27, v40, v27
	global_store_dwordx4 v[36:37], v[24:27], off
	s_or_b64 exec, exec, s[96:97]
	s_and_saveexec_b64 s[0:1], s[10:11]
	s_xor_b64 s[96:97], exec, s[0:1]
	s_cbranch_execz .LBB0_374
.LBB0_393:
	v_mov_b32_e32 v121, v137
	v_pk_add_f32 v[16:17], v[16:17], v[178:179]
	v_pk_add_f32 v[20:21], v[20:21], v[174:175]
	v_pk_add_f32 v[26:27], v[18:19], v[180:181]
	v_mul_f32_e32 v18, 0xbfb8aa3b, v20
	v_mul_f32_e32 v16, 0xbfb8aa3b, v16
	v_exp_f32_e32 v20, v18
	v_mul_f32_e32 v18, 0xbfb8aa3b, v21
	v_exp_f32_e32 v21, v16
	v_pk_add_f32 v[22:23], v[22:23], v[176:177]
	v_mul_f32_e32 v16, 0xbfb8aa3b, v17
	v_exp_f32_e32 v24, v18
	v_mul_f32_e32 v18, 0xbfb8aa3b, v22
	v_exp_f32_e32 v25, v16
	v_mul_f32_e32 v16, 0xbfb8aa3b, v26
	v_exp_f32_e32 v22, v18
	v_mul_f32_e32 v18, 0xbfb8aa3b, v23
	v_exp_f32_e32 v23, v16
	v_mul_f32_e32 v16, 0xbfb8aa3b, v27
	v_exp_f32_e32 v19, v16
	v_pk_add_f32 v[16:17], v[20:21], 1.0 op_sel_hi:[1,0]
	v_pk_add_f32 v[22:23], v[22:23], 1.0 op_sel_hi:[1,0]
	v_exp_f32_e32 v18, v18
	v_rcp_f32_e32 v17, v17
	v_pk_add_f32 v[18:19], v[18:19], 1.0 op_sel_hi:[1,0]
	v_rcp_f32_e32 v16, v16
	v_pk_add_f32 v[20:21], v[24:25], 1.0 op_sel_hi:[1,0]
	v_pk_fma_f32 v[16:17], v[16:17], s[28:29], 0.5 op_sel_hi:[1,0,0]
	v_rcp_f32_e32 v21, v21
	v_rcp_f32_e32 v20, v20
	v_rcp_f32_e32 v23, v23
	v_rcp_f32_e32 v22, v22
	v_rcp_f32_e32 v19, v19
	v_rcp_f32_e32 v18, v18
	v_cvt_u32_f32_e32 v24, v17
	v_cvt_u32_f32_e32 v25, v16
	v_pk_fma_f32 v[16:17], v[20:21], s[28:29], 0.5 op_sel_hi:[1,0,0]
	s_nop 0
	v_cvt_u32_f32_e32 v16, v16
	v_cvt_u32_f32_e32 v17, v17
	v_lshlrev_b32_e32 v16, 8, v16
	v_lshlrev_b32_e32 v17, 8, v17
	v_or_b32_e32 v20, v17, v24
	v_or_b32_e32 v21, v16, v25
	v_pk_fma_f32 v[16:17], v[22:23], s[28:29], 0.5 op_sel_hi:[1,0,0]
	s_nop 0
	v_cvt_u32_f32_sdwa v16, v16 dst_sel:WORD_1 dst_unused:UNUSED_PAD src0_sel:DWORD
	v_cvt_u32_f32_sdwa v17, v17 dst_sel:WORD_1 dst_unused:UNUSED_PAD src0_sel:DWORD
	v_or_b32_e32 v21, v21, v16
	v_or_b32_e32 v20, v20, v17
	v_pk_fma_f32 v[16:17], v[18:19], s[28:29], 0.5 op_sel_hi:[1,0,0]
	v_lshl_add_u64 v[18:19], v[32:33], 0, v[120:121]
	v_cvt_u32_f32_sdwa v16, v16 dst_sel:BYTE_3 dst_unused:UNUSED_PAD src0_sel:DWORD
	v_cvt_u32_f32_sdwa v17, v17 dst_sel:BYTE_3 dst_unused:UNUSED_PAD src0_sel:DWORD
	v_or_b32_e32 v16, v21, v16
	v_or_b32_e32 v17, v20, v17
	global_store_dwordx2 v[18:19], v[16:17], off
	s_andn2_saveexec_b64 s[96:97], s[96:97]
	s_cbranch_execnz .LBB0_375
	s_branch .LBB0_376
.LBB0_394:
	v_pk_add_f32 v[8:9], v[8:9], v[170:171]
	v_pk_add_f32 v[12:13], v[12:13], v[166:167]
	v_pk_add_f32 v[10:11], v[10:11], v[172:173]
	v_mul_f32_e32 v12, 0xbfb8aa3b, v12
	v_exp_f32_e32 v12, v12
	v_mul_f32_e32 v13, 0xbfb8aa3b, v13
	v_exp_f32_e32 v13, v13
	v_pk_add_f32 v[14:15], v[14:15], v[168:169]
	v_add_f32_e32 v12, 1.0, v12
	v_add_f32_e32 v13, 1.0, v13
	v_mul_f32_e32 v14, 0xbfb8aa3b, v14
	v_exp_f32_e32 v14, v14
	v_rcp_f32_e32 v12, v12
	v_add_f32_e32 v14, 1.0, v14
	v_mul_f32_e32 v15, 0xbfb8aa3b, v15
	v_exp_f32_e32 v15, v15
	v_rcp_f32_e32 v13, v13
	v_add_f32_e32 v15, 1.0, v15
	v_mul_f32_e32 v8, 0xbfb8aa3b, v8
	v_exp_f32_e32 v8, v8
	v_rcp_f32_e32 v14, v14
	v_add_f32_e32 v8, 1.0, v8
	v_mul_f32_e32 v12, 0xbf60028a, v12
	v_mul_f32_e32 v13, 0xbf60028a, v13
	v_rcp_f32_e32 v15, v15
	v_mul_f32_e32 v14, 0xbf60028a, v14
	v_mul_f32_e32 v15, 0xbf60028a, v15
	v_rcp_f32_e32 v8, v8
	s_nop 0
	v_mul_f32_e32 v22, 0xbf60028a, v8
	v_mul_f32_e32 v8, 0xbfb8aa3b, v9
	v_exp_f32_e32 v8, v8
	s_nop 0
	v_add_f32_e32 v8, 1.0, v8
	v_rcp_f32_e32 v8, v8
	s_nop 0
	v_mul_f32_e32 v23, 0xbf60028a, v8
	v_mul_f32_e32 v8, 0xbfb8aa3b, v10
	v_exp_f32_e32 v8, v8
	s_nop 0
	v_add_f32_e32 v8, 1.0, v8
	v_rcp_f32_e32 v8, v8
	s_nop 0
	v_mul_f32_e32 v24, 0xbf60028a, v8
	v_mul_f32_e32 v8, 0xbfb8aa3b, v11
	v_exp_f32_e32 v8, v8
	s_nop 0
	v_add_f32_e32 v8, 1.0, v8
	v_rcp_f32_e32 v8, v8
	s_nop 0
	v_mul_f32_e32 v11, 0xbf60028a, v8
	v_lshl_add_u64 v[20:21], v[142:143], 1, v[18:19]
	v_cvt_pk_bf16_f32 v8, v12, v13
	v_cvt_pk_bf16_f32 v9, v14, v15
	v_cvt_pk_bf16_f32 v10, v22, v23
	v_cvt_pk_bf16_f32 v11, v24, v11
	global_store_dwordx4 v[20:21], v[8:11], off
	s_or_b64 exec, exec, s[8:9]
	s_and_saveexec_b64 s[0:1], s[10:11]
	s_xor_b64 s[8:9], exec, s[0:1]
	s_cbranch_execz .LBB0_380
.LBB0_395:
	v_mov_b32_e32 v121, v137
	v_pk_add_f32 v[0:1], v[0:1], v[178:179]
	v_pk_add_f32 v[4:5], v[4:5], v[174:175]
	v_pk_add_f32 v[10:11], v[2:3], v[180:181]
	v_mul_f32_e32 v2, 0xbfb8aa3b, v4
	v_mul_f32_e32 v0, 0xbfb8aa3b, v0
	v_exp_f32_e32 v4, v2
	v_mul_f32_e32 v2, 0xbfb8aa3b, v5
	v_exp_f32_e32 v5, v0
	v_pk_add_f32 v[6:7], v[6:7], v[176:177]
	v_mul_f32_e32 v0, 0xbfb8aa3b, v1
	v_exp_f32_e32 v8, v2
	v_mul_f32_e32 v2, 0xbfb8aa3b, v6
	v_exp_f32_e32 v9, v0
	v_mul_f32_e32 v0, 0xbfb8aa3b, v10
	v_exp_f32_e32 v6, v2
	v_mul_f32_e32 v2, 0xbfb8aa3b, v7
	v_exp_f32_e32 v7, v0
	v_mul_f32_e32 v0, 0xbfb8aa3b, v11
	v_exp_f32_e32 v3, v0
	v_pk_add_f32 v[0:1], v[4:5], 1.0 op_sel_hi:[1,0]
	v_pk_add_f32 v[6:7], v[6:7], 1.0 op_sel_hi:[1,0]
	v_exp_f32_e32 v2, v2
	v_rcp_f32_e32 v1, v1
	v_pk_add_f32 v[2:3], v[2:3], 1.0 op_sel_hi:[1,0]
	v_rcp_f32_e32 v0, v0
	v_pk_add_f32 v[4:5], v[8:9], 1.0 op_sel_hi:[1,0]
	v_pk_fma_f32 v[0:1], v[0:1], s[28:29], 0.5 op_sel_hi:[1,0,0]
	v_rcp_f32_e32 v5, v5
	v_rcp_f32_e32 v4, v4
	v_rcp_f32_e32 v7, v7
	v_rcp_f32_e32 v6, v6
	v_rcp_f32_e32 v3, v3
	v_rcp_f32_e32 v2, v2
	v_cvt_u32_f32_e32 v8, v1
	v_cvt_u32_f32_e32 v9, v0
	v_pk_fma_f32 v[0:1], v[4:5], s[28:29], 0.5 op_sel_hi:[1,0,0]
	s_nop 0
	v_cvt_u32_f32_e32 v0, v0
	v_cvt_u32_f32_e32 v1, v1
	v_lshlrev_b32_e32 v0, 8, v0
	v_lshlrev_b32_e32 v1, 8, v1
	v_or_b32_e32 v4, v1, v8
	v_or_b32_e32 v5, v0, v9
	v_pk_fma_f32 v[0:1], v[6:7], s[28:29], 0.5 op_sel_hi:[1,0,0]
	s_nop 0
	v_cvt_u32_f32_sdwa v0, v0 dst_sel:WORD_1 dst_unused:UNUSED_PAD src0_sel:DWORD
	v_cvt_u32_f32_sdwa v1, v1 dst_sel:WORD_1 dst_unused:UNUSED_PAD src0_sel:DWORD
	v_or_b32_e32 v5, v5, v0
	v_or_b32_e32 v4, v4, v1
	v_pk_fma_f32 v[0:1], v[2:3], s[28:29], 0.5 op_sel_hi:[1,0,0]
	v_lshl_add_u64 v[2:3], v[16:17], 0, v[120:121]
	v_cvt_u32_f32_sdwa v0, v0 dst_sel:BYTE_3 dst_unused:UNUSED_PAD src0_sel:DWORD
	v_cvt_u32_f32_sdwa v1, v1 dst_sel:BYTE_3 dst_unused:UNUSED_PAD src0_sel:DWORD
	v_or_b32_e32 v0, v5, v0
	v_or_b32_e32 v1, v4, v1
	global_store_dwordx2 v[2:3], v[0:1], off
	s_andn2_saveexec_b64 s[8:9], s[8:9]
	s_cbranch_execz .LBB0_381
.LBB0_396:
	v_pk_add_f32 v[0:1], v[0:1], v[178:179]
	v_pk_add_f32 v[4:5], v[4:5], v[174:175]
	v_pk_add_f32 v[2:3], v[2:3], v[180:181]
	v_mul_f32_e32 v4, 0xbfb8aa3b, v4
	v_exp_f32_e32 v4, v4
	v_mul_f32_e32 v5, 0xbfb8aa3b, v5
	v_exp_f32_e32 v5, v5
	v_pk_add_f32 v[6:7], v[6:7], v[176:177]
	v_add_f32_e32 v4, 1.0, v4
	v_add_f32_e32 v5, 1.0, v5
	v_mul_f32_e32 v6, 0xbfb8aa3b, v6
	v_exp_f32_e32 v6, v6
	v_rcp_f32_e32 v4, v4
	v_add_f32_e32 v6, 1.0, v6
	v_mul_f32_e32 v7, 0xbfb8aa3b, v7
	v_exp_f32_e32 v7, v7
	v_rcp_f32_e32 v5, v5
	v_add_f32_e32 v7, 1.0, v7
	v_mul_f32_e32 v0, 0xbfb8aa3b, v0
	v_exp_f32_e32 v0, v0
	v_rcp_f32_e32 v6, v6
	v_add_f32_e32 v0, 1.0, v0
	v_mul_f32_e32 v4, 0xbf60028a, v4
	v_mul_f32_e32 v5, 0xbf60028a, v5
	v_rcp_f32_e32 v7, v7
	v_mul_f32_e32 v6, 0xbf60028a, v6
	v_mul_f32_e32 v7, 0xbf60028a, v7
	v_rcp_f32_e32 v0, v0
	s_nop 0
	v_mul_f32_e32 v10, 0xbf60028a, v0
	v_mul_f32_e32 v0, 0xbfb8aa3b, v1
	v_exp_f32_e32 v0, v0
	s_nop 0
	v_add_f32_e32 v0, 1.0, v0
	v_rcp_f32_e32 v0, v0
	s_nop 0
	v_mul_f32_e32 v11, 0xbf60028a, v0
	v_mul_f32_e32 v0, 0xbfb8aa3b, v2
	v_exp_f32_e32 v0, v0
	s_nop 0
	v_add_f32_e32 v0, 1.0, v0
	v_rcp_f32_e32 v0, v0
	s_nop 0
	v_mul_f32_e32 v12, 0xbf60028a, v0
	v_mul_f32_e32 v0, 0xbfb8aa3b, v3
	v_exp_f32_e32 v0, v0
	s_nop 0
	v_add_f32_e32 v0, 1.0, v0
	v_rcp_f32_e32 v0, v0
	s_nop 0
	v_mul_f32_e32 v3, 0xbf60028a, v0
	v_lshl_add_u64 v[8:9], v[142:143], 1, v[18:19]
	v_cvt_pk_bf16_f32 v0, v4, v5
	v_cvt_pk_bf16_f32 v1, v6, v7
	v_cvt_pk_bf16_f32 v2, v10, v11
	v_cvt_pk_bf16_f32 v3, v12, v3
	global_store_dwordx4 v[8:9], v[0:3], off offset:256
	s_or_b64 exec, exec, s[8:9]
	s_andn2_b64 vcc, exec, s[6:7]
	s_mov_b64 s[0:1], -1
	s_cbranch_vccnz .LBB0_323
